# loop-edge edit: the K-loop's loop-control SALU block moved ahead of the iteration-closing barrier in six GEMM phases
# baseline (speedup 1.0000x reference)
; #define PG8_STAGE(bufoff, gbase, voff) do { _Pragma("unroll") for (int _i = 0; _i < 2; ++_i) \
;         __builtin_amdgcn_global_load_lds((const unsigned*)((const char*)(gbase) + (voff)[_i]), (LAS unsigned*)(lds + (bufoff) + ldsw + _i * 8192), 16, 0, 0); } while (0)
; #define PG8_LDA(dst, b, h) do { _Pragma("unroll") for (int m = 0; m < 4; ++m) _Pragma("unroll") for (int k = 0; k < 2; ++k) dst[m][k] = *(const LAS bf16x8*)(lds + PG8_SA(b, h) + aoff + m * 2048 + k * 1024); } while (0)
; #define PG8_LDB(dst, b, h) do { _Pragma("unroll") for (int n = 0; n < 2; ++n) _Pragma("unroll") for (int k = 0; k < 2; ++k) dst[n][k] = *(const LAS bf16x8*)(lds + PG8_SB(b, h) + boff + n * 2048 + k * 1024); } while (0)
; #define PG8_BAR __builtin_amdgcn_s_barrier()
; template <class Sched, class Epi, bool ALIGN_EPI, bool SP2>
; __device__ __forceinline__ void gemm_phase(LAS unsigned char* lds, const int K, const int lda, const int ldb, const Sched& S, const Epi& E) {
;     ...
;         for (int t = 0; t < nt; t += 2) {
;             const bool last = (t == nt - 2);
;             const char* a1 = cA + (size_t)(t + 1) * kstep;
;             const char* a2 = last ? nA : cA + (size_t)(t + 2) * kstep; const char* b2 = last ? nB : cB + (size_t)(t + 2) * kstep;
;             const char* a3 = a2 + kstep; const char* b3 = b2 + kstep;
;             if constexpr (SP2) {
;             PG8_LDB(B0, 0, 0); PG8_LDB(B1, 0, 1); PG8_SCHED; PG8_LDA(At, 0, 0); PG8_STAGE(PG8_SA(1, 1), a1 + hstepA, voffA);
;             PG8_WAIT_V(8); PG8_WAIT_L(0); PG8_BAR; PG8_MMA(0, 0, At, B0); PG8_MMA(0, 1, At, B1); PG8_BAR; PG8_SCHED;
;             PG8_LDA(At, 0, 1); PG8_STAGE(PG8_SB(0, 0), b2, voffB); PG8_STAGE(PG8_SB(0, 1), b2 + hstepB, voffB); PG8_STAGE(PG8_SA(0, 0), a2, voffA);
;             PG8_WAIT_V(8); PG8_WAIT_L(0); PG8_BAR; PG8_MMA(1, 0, At, B0); PG8_MMA(1, 1, At, B1); PG8_BAR; PG8_SCHED;
;             PG8_LDB(B0, 1, 0); PG8_LDB(B1, 1, 1); PG8_SCHED; PG8_LDA(At, 1, 0); PG8_STAGE(PG8_SA(0, 1), a2 + hstepA, voffA);
;             PG8_WAIT_V(8); PG8_WAIT_L(0); PG8_BAR; PG8_MMA(0, 0, At, B0); PG8_MMA(0, 1, At, B1); PG8_BAR; PG8_SCHED;
;             PG8_LDA(At, 1, 1); PG8_STAGE(PG8_SB(1, 0), b3, voffB); PG8_STAGE(PG8_SB(1, 1), b3 + hstepB, voffB); PG8_STAGE(PG8_SA(1, 0), a3, voffA);
;             PG8_WAIT_V(8); PG8_WAIT_L(0); PG8_BAR; PG8_MMA(1, 0, At, B0); PG8_MMA(1, 1, At, B1); PG8_BAR; PG8_SCHED;
.LBB0_155:
	ds_read_b128 v[140:143], v147
	ds_read_b128 v[150:153], v147 offset:1024
	ds_read_b128 v[154:157], v147 offset:2048
	ds_read_b128 v[158:161], v147 offset:3072
	ds_read_b128 v[162:165], v148
	ds_read_b128 v[166:169], v148 offset:1024
	ds_read_b128 v[170:173], v148 offset:2048
	ds_read_b128 v[180:183], v148 offset:3072
	s_add_u32 s22, s20, 0xfff80080
	s_addc_u32 s23, s21, -1
	s_cmp_eq_u32 s75, 28
	s_cselect_b32 s25, s15, s23
	s_cselect_b32 s24, s14, s22
	s_cselect_b32 s23, s17, s74
	s_cselect_b32 s22, s16, s13
	v_lshl_add_u64 v[174:175], s[20:21], 0, v[136:137]
	s_add_i32 m0, s3, 0xc000
	ds_read_b128 v[184:187], v149
	ds_read_b128 v[188:191], v149 offset:1024
	ds_read_b128 v[192:195], v149 offset:2048
	ds_read_b128 v[196:199], v149 offset:3072
	ds_read_b128 v[200:203], v149 offset:4096
	ds_read_b128 v[204:207], v149 offset:5120
	ds_read_b128 v[208:211], v149 offset:6144
	ds_read_b128 v[212:215], v149 offset:7168
	global_load_lds_dwordx4 v[174:175], off
	v_lshl_add_u64 v[174:175], s[20:21], 0, v[138:139]
	s_add_i32 m0, s3, 0xe000
	s_nop 0
	global_load_lds_dwordx4 v[174:175], off
	s_waitcnt vmcnt(8)
	s_waitcnt lgkmcnt(0)
	s_barrier
	s_setprio 1
	s_waitcnt lgkmcnt(0)
	v_mfma_f32_16x16x32_bf16 v[124:127], v[140:143], v[184:187], v[124:127]
	v_mfma_f32_16x16x32_bf16 v[120:123], v[154:157], v[184:187], v[120:123]
	v_mfma_f32_16x16x32_bf16 v[108:111], v[140:143], v[192:195], v[108:111]
	v_mfma_f32_16x16x32_bf16 v[104:107], v[154:157], v[192:195], v[104:107]
	v_mfma_f32_16x16x32_bf16 v[92:95], v[140:143], v[200:203], v[92:95]
	v_mfma_f32_16x16x32_bf16 v[88:91], v[154:157], v[200:203], v[88:91]
	v_mfma_f32_16x16x32_bf16 v[76:79], v[140:143], v[208:211], v[76:79]
	v_mfma_f32_16x16x32_bf16 v[72:75], v[154:157], v[208:211], v[72:75]
	v_mfma_f32_16x16x32_bf16 v[124:127], v[150:153], v[188:191], v[124:127]
	v_mfma_f32_16x16x32_bf16 v[120:123], v[158:161], v[188:191], v[120:123]
	v_mfma_f32_16x16x32_bf16 v[108:111], v[150:153], v[196:199], v[108:111]
	v_mfma_f32_16x16x32_bf16 v[104:107], v[158:161], v[196:199], v[104:107]
	v_mfma_f32_16x16x32_bf16 v[92:95], v[150:153], v[204:207], v[92:95]
	v_mfma_f32_16x16x32_bf16 v[88:91], v[158:161], v[204:207], v[88:91]
	v_mfma_f32_16x16x32_bf16 v[76:79], v[150:153], v[212:215], v[76:79]
	v_mfma_f32_16x16x32_bf16 v[72:75], v[158:161], v[212:215], v[72:75]
	s_setprio 0
	s_setprio 1
	v_mfma_f32_16x16x32_bf16 v[116:119], v[162:165], v[184:187], v[116:119]
	v_mfma_f32_16x16x32_bf16 v[112:115], v[170:173], v[184:187], v[112:115]
	v_mfma_f32_16x16x32_bf16 v[100:103], v[162:165], v[192:195], v[100:103]
	v_mfma_f32_16x16x32_bf16 v[96:99], v[170:173], v[192:195], v[96:99]
	v_mfma_f32_16x16x32_bf16 v[84:87], v[162:165], v[200:203], v[84:87]
	v_mfma_f32_16x16x32_bf16 v[80:83], v[170:173], v[200:203], v[80:83]
	v_mfma_f32_16x16x32_bf16 v[68:71], v[162:165], v[208:211], v[68:71]
	v_mfma_f32_16x16x32_bf16 v[64:67], v[170:173], v[208:211], v[64:67]
	v_mfma_f32_16x16x32_bf16 v[116:119], v[166:169], v[188:191], v[116:119]
	v_mfma_f32_16x16x32_bf16 v[112:115], v[180:183], v[188:191], v[112:115]
	v_mfma_f32_16x16x32_bf16 v[100:103], v[166:169], v[196:199], v[100:103]
	v_mfma_f32_16x16x32_bf16 v[96:99], v[180:183], v[196:199], v[96:99]
	v_mfma_f32_16x16x32_bf16 v[84:87], v[166:169], v[204:207], v[84:87]
	v_mfma_f32_16x16x32_bf16 v[80:83], v[180:183], v[204:207], v[80:83]
	v_mfma_f32_16x16x32_bf16 v[68:71], v[166:169], v[212:215], v[68:71]
	v_mfma_f32_16x16x32_bf16 v[64:67], v[180:183], v[212:215], v[64:67]
	s_setprio 0
	s_barrier
	s_add_i32 s78, s35, s2
	v_lshl_add_u64 v[174:175], s[22:23], 0, v[130:131]
	s_mov_b32 m0, s78
	ds_read_b128 v[184:187], v149 offset:16384
	ds_read_b128 v[188:191], v149 offset:17408
	ds_read_b128 v[192:195], v149 offset:18432
	ds_read_b128 v[196:199], v149 offset:19456
	ds_read_b128 v[200:203], v149 offset:20480
	ds_read_b128 v[204:207], v149 offset:21504
	ds_read_b128 v[208:211], v149 offset:22528
	ds_read_b128 v[212:215], v149 offset:23552
	global_load_lds_dwordx4 v[174:175], off
	s_add_i32 m0, s78, 0x2000
	s_add_u32 s78, s22, 0x80000
	v_lshl_add_u64 v[216:217], s[22:23], 0, v[134:135]
	s_addc_u32 s79, s23, 0
	s_add_i32 s84, s50, s2
	global_load_lds_dwordx4 v[216:217], off
	v_lshl_add_u64 v[218:219], s[78:79], 0, v[130:131]
	s_mov_b32 m0, s84
	v_lshl_add_u64 v[220:221], s[24:25], 0, v[132:133]
	global_load_lds_dwordx4 v[218:219], off
	v_lshl_add_u64 v[218:219], s[78:79], 0, v[134:135]
	s_add_i32 m0, s84, 0x2000
	s_nop 0
	global_load_lds_dwordx4 v[218:219], off
	v_lshl_add_u64 v[218:219], s[24:25], 0, v[128:129]
	s_mov_b32 m0, s3
	s_nop 0
	global_load_lds_dwordx4 v[218:219], off
	s_mov_b32 m0, s19
	s_nop 0
	global_load_lds_dwordx4 v[220:221], off
	s_waitcnt vmcnt(8)
	s_waitcnt lgkmcnt(0)
	s_barrier
; #define PG8_STAGE(bufoff, gbase, voff) do { _Pragma("unroll") for (int _i = 0; _i < 2; ++_i) \
;         __builtin_amdgcn_global_load_lds((const unsigned*)((const char*)(gbase) + (voff)[_i]), (LAS unsigned*)(lds + (bufoff) + ldsw + _i * 8192), 16, 0, 0); } while (0)
; #define PG8_LDA(dst, b, h) do { _Pragma("unroll") for (int m = 0; m < 4; ++m) _Pragma("unroll") for (int k = 0; k < 2; ++k) dst[m][k] = *(const LAS bf16x8*)(lds + PG8_SA(b, h) + aoff + m * 2048 + k * 1024); } while (0)
; #define PG8_LDB(dst, b, h) do { _Pragma("unroll") for (int n = 0; n < 2; ++n) _Pragma("unroll") for (int k = 0; k < 2; ++k) dst[n][k] = *(const LAS bf16x8*)(lds + PG8_SB(b, h) + boff + n * 2048 + k * 1024); } while (0)
; #define PG8_MMA(ai, bj, At, Bt) do { __builtin_amdgcn_s_setprio(1); _Pragma("unroll") for (int m = 0; m < 4; ++m) _Pragma("unroll") for (int n = 0; n < 2; ++n) _Pragma("unroll") for (int k = 0; k < 2; ++k) \
;         acc[ai][bj][m][n] = __builtin_amdgcn_mfma_f32_16x16x32_bf16(Bt[n][k], At[m][k], acc[ai][bj][m][n], 0, 0, 0); __builtin_amdgcn_s_setprio(0); } while (0)
; #define PG8_WAIT_V(n) asm volatile("s_waitcnt vmcnt(" #n ")" ::: "memory")
; template <class Sched, class Epi, bool ALIGN_EPI, bool SP2>
; __device__ __forceinline__ void gemm_phase(LAS unsigned char* lds, const int K, const int lda, const int ldb, const Sched& S, const Epi& E) {
;     ...
;             PG8_LDB(B0, 0, 0); PG8_LDB(B1, 0, 1); PG8_SCHED; PG8_LDA(At, 0, 0); PG8_STAGE(PG8_SA(1, 1), a1 + hstepA, voffA);
;             PG8_WAIT_V(8); PG8_WAIT_L(0); PG8_BAR; PG8_MMA(0, 0, At, B0); PG8_MMA(0, 1, At, B1); PG8_BAR; PG8_SCHED;
;             PG8_LDA(At, 0, 1); PG8_STAGE(PG8_SB(0, 0), b2, voffB); PG8_STAGE(PG8_SB(0, 1), b2 + hstepB, voffB); PG8_STAGE(PG8_SA(0, 0), a2, voffA);
;             PG8_WAIT_V(8); PG8_WAIT_L(0); PG8_BAR; PG8_MMA(1, 0, At, B0); PG8_MMA(1, 1, At, B1); PG8_BAR; PG8_SCHED;
;             PG8_LDB(B0, 1, 0); PG8_LDB(B1, 1, 1); PG8_SCHED; PG8_LDA(At, 1, 0); PG8_STAGE(PG8_SA(0, 1), a2 + hstepA, voffA);
;             PG8_WAIT_V(8); PG8_WAIT_L(0); PG8_BAR; PG8_MMA(0, 0, At, B0); PG8_MMA(0, 1, At, B1); PG8_BAR; PG8_SCHED;
;             PG8_LDA(At, 1, 1); PG8_STAGE(PG8_SB(1, 0), b3, voffB); PG8_STAGE(PG8_SB(1, 1), b3 + hstepB, voffB); PG8_STAGE(PG8_SA(1, 0), a3, voffA);
;             PG8_WAIT_V(8); PG8_WAIT_L(0); PG8_BAR; PG8_MMA(1, 0, At, B0); PG8_MMA(1, 1, At, B1); PG8_BAR; PG8_SCHED;
	s_setprio 1
	s_waitcnt lgkmcnt(0)
	v_mfma_f32_16x16x32_bf16 v[60:63], v[140:143], v[184:187], v[60:63]
	v_mfma_f32_16x16x32_bf16 v[56:59], v[154:157], v[184:187], v[56:59]
	v_mfma_f32_16x16x32_bf16 v[44:47], v[140:143], v[192:195], v[44:47]
	v_mfma_f32_16x16x32_bf16 v[40:43], v[154:157], v[192:195], v[40:43]
	v_mfma_f32_16x16x32_bf16 v[28:31], v[140:143], v[200:203], v[28:31]
	v_mfma_f32_16x16x32_bf16 v[24:27], v[154:157], v[200:203], v[24:27]
	v_mfma_f32_16x16x32_bf16 v[12:15], v[140:143], v[208:211], v[12:15]
	v_mfma_f32_16x16x32_bf16 v[8:11], v[154:157], v[208:211], v[8:11]
	v_mfma_f32_16x16x32_bf16 v[60:63], v[150:153], v[188:191], v[60:63]
	v_mfma_f32_16x16x32_bf16 v[56:59], v[158:161], v[188:191], v[56:59]
	v_mfma_f32_16x16x32_bf16 v[44:47], v[150:153], v[196:199], v[44:47]
	v_mfma_f32_16x16x32_bf16 v[40:43], v[158:161], v[196:199], v[40:43]
	v_mfma_f32_16x16x32_bf16 v[28:31], v[150:153], v[204:207], v[28:31]
	v_mfma_f32_16x16x32_bf16 v[24:27], v[158:161], v[204:207], v[24:27]
	v_mfma_f32_16x16x32_bf16 v[12:15], v[150:153], v[212:215], v[12:15]
	v_mfma_f32_16x16x32_bf16 v[8:11], v[158:161], v[212:215], v[8:11]
	s_setprio 0
	s_setprio 1
	v_mfma_f32_16x16x32_bf16 v[52:55], v[162:165], v[184:187], v[52:55]
	v_mfma_f32_16x16x32_bf16 v[48:51], v[170:173], v[184:187], v[48:51]
	v_mfma_f32_16x16x32_bf16 v[36:39], v[162:165], v[192:195], v[36:39]
	v_mfma_f32_16x16x32_bf16 v[32:35], v[170:173], v[192:195], v[32:35]
	v_mfma_f32_16x16x32_bf16 v[20:23], v[162:165], v[200:203], v[20:23]
	v_mfma_f32_16x16x32_bf16 v[16:19], v[170:173], v[200:203], v[16:19]
	v_mfma_f32_16x16x32_bf16 v[4:7], v[162:165], v[208:211], v[4:7]
	v_mfma_f32_16x16x32_bf16 v[0:3], v[170:173], v[208:211], v[0:3]
	v_mfma_f32_16x16x32_bf16 v[52:55], v[166:169], v[188:191], v[52:55]
	v_mfma_f32_16x16x32_bf16 v[48:51], v[180:183], v[188:191], v[48:51]
	v_mfma_f32_16x16x32_bf16 v[36:39], v[166:169], v[196:199], v[36:39]
	v_mfma_f32_16x16x32_bf16 v[32:35], v[180:183], v[196:199], v[32:35]
	v_mfma_f32_16x16x32_bf16 v[20:23], v[166:169], v[204:207], v[20:23]
	v_mfma_f32_16x16x32_bf16 v[16:19], v[180:183], v[204:207], v[16:19]
	v_mfma_f32_16x16x32_bf16 v[4:7], v[166:169], v[212:215], v[4:7]
	v_mfma_f32_16x16x32_bf16 v[0:3], v[180:183], v[212:215], v[0:3]
	s_setprio 0
	s_barrier
	s_add_i32 s78, 0, 0x18000
	s_add_i32 s79, 0, 0x1c000
	v_add_u32_e32 v158, s78, v145
	v_add_u32_e32 v177, s79, v145
	ds_read_b128 v[140:143], v158
	ds_read_b128 v[150:153], v158 offset:1024
	ds_read_b128 v[154:157], v158 offset:2048
	ds_read_b128 v[158:161], v158 offset:3072
	ds_read_b128 v[162:165], v177
	ds_read_b128 v[166:169], v177 offset:1024
	ds_read_b128 v[170:173], v177 offset:2048
	ds_read_b128 v[180:183], v177 offset:3072
	s_add_u32 s24, s24, 0x80000
	s_addc_u32 s25, s25, 0
	s_mov_b32 m0, s26
	v_lshl_add_u64 v[222:223], s[24:25], 0, v[128:129]
	ds_read_b128 v[184:187], v149 offset:32768
	ds_read_b128 v[188:191], v149 offset:33792
	ds_read_b128 v[192:195], v149 offset:34816
	ds_read_b128 v[196:199], v149 offset:35840
	ds_read_b128 v[200:203], v149 offset:36864
	ds_read_b128 v[204:207], v149 offset:37888
	ds_read_b128 v[208:211], v149 offset:38912
	ds_read_b128 v[212:215], v149 offset:39936
	global_load_lds_dwordx4 v[222:223], off
	v_lshl_add_u64 v[222:223], s[24:25], 0, v[132:133]
	s_mov_b32 m0, s27
	s_nop 0
	global_load_lds_dwordx4 v[222:223], off
	s_waitcnt vmcnt(8)
	s_waitcnt lgkmcnt(0)
	s_barrier
	s_setprio 1
	s_waitcnt lgkmcnt(0)
	v_mfma_f32_16x16x32_bf16 v[124:127], v[140:143], v[184:187], v[124:127]
	v_mfma_f32_16x16x32_bf16 v[120:123], v[154:157], v[184:187], v[120:123]
	v_mfma_f32_16x16x32_bf16 v[108:111], v[140:143], v[192:195], v[108:111]
	v_mfma_f32_16x16x32_bf16 v[104:107], v[154:157], v[192:195], v[104:107]
	v_mfma_f32_16x16x32_bf16 v[92:95], v[140:143], v[200:203], v[92:95]
	v_mfma_f32_16x16x32_bf16 v[88:91], v[154:157], v[200:203], v[88:91]
	v_mfma_f32_16x16x32_bf16 v[76:79], v[140:143], v[208:211], v[76:79]
	v_mfma_f32_16x16x32_bf16 v[72:75], v[154:157], v[208:211], v[72:75]
	v_mfma_f32_16x16x32_bf16 v[124:127], v[150:153], v[188:191], v[124:127]
	v_mfma_f32_16x16x32_bf16 v[120:123], v[158:161], v[188:191], v[120:123]
	v_mfma_f32_16x16x32_bf16 v[108:111], v[150:153], v[196:199], v[108:111]
	v_mfma_f32_16x16x32_bf16 v[104:107], v[158:161], v[196:199], v[104:107]
	v_mfma_f32_16x16x32_bf16 v[92:95], v[150:153], v[204:207], v[92:95]
	v_mfma_f32_16x16x32_bf16 v[88:91], v[158:161], v[204:207], v[88:91]
	v_mfma_f32_16x16x32_bf16 v[76:79], v[150:153], v[212:215], v[76:79]
	v_mfma_f32_16x16x32_bf16 v[72:75], v[158:161], v[212:215], v[72:75]
	s_setprio 0
	s_setprio 1
	v_mfma_f32_16x16x32_bf16 v[116:119], v[162:165], v[184:187], v[116:119]
	v_mfma_f32_16x16x32_bf16 v[112:115], v[170:173], v[184:187], v[112:115]
	v_mfma_f32_16x16x32_bf16 v[100:103], v[162:165], v[192:195], v[100:103]
	v_mfma_f32_16x16x32_bf16 v[96:99], v[170:173], v[192:195], v[96:99]
	v_mfma_f32_16x16x32_bf16 v[84:87], v[162:165], v[200:203], v[84:87]
	v_mfma_f32_16x16x32_bf16 v[80:83], v[170:173], v[200:203], v[80:83]
	v_mfma_f32_16x16x32_bf16 v[68:71], v[162:165], v[208:211], v[68:71]
	v_mfma_f32_16x16x32_bf16 v[64:67], v[170:173], v[208:211], v[64:67]
	v_mfma_f32_16x16x32_bf16 v[116:119], v[166:169], v[188:191], v[116:119]
	v_mfma_f32_16x16x32_bf16 v[112:115], v[180:183], v[188:191], v[112:115]
	v_mfma_f32_16x16x32_bf16 v[100:103], v[166:169], v[196:199], v[100:103]
	v_mfma_f32_16x16x32_bf16 v[96:99], v[180:183], v[196:199], v[96:99]
	v_mfma_f32_16x16x32_bf16 v[84:87], v[166:169], v[204:207], v[84:87]
	v_mfma_f32_16x16x32_bf16 v[80:83], v[180:183], v[204:207], v[80:83]
	v_mfma_f32_16x16x32_bf16 v[68:71], v[166:169], v[212:215], v[68:71]
	v_mfma_f32_16x16x32_bf16 v[64:67], v[180:183], v[212:215], v[64:67]
	s_setprio 0
	s_barrier
; #define PG8_STAGE(bufoff, gbase, voff) do { _Pragma("unroll") for (int _i = 0; _i < 2; ++_i) \
;         __builtin_amdgcn_global_load_lds((const unsigned*)((const char*)(gbase) + (voff)[_i]), (LAS unsigned*)(lds + (bufoff) + ldsw + _i * 8192), 16, 0, 0); } while (0)
; #define PG8_LDA(dst, b, h) do { _Pragma("unroll") for (int m = 0; m < 4; ++m) _Pragma("unroll") for (int k = 0; k < 2; ++k) dst[m][k] = *(const LAS bf16x8*)(lds + PG8_SA(b, h) + aoff + m * 2048 + k * 1024); } while (0)
; #define PG8_MMA(ai, bj, At, Bt) do { __builtin_amdgcn_s_setprio(1); _Pragma("unroll") for (int m = 0; m < 4; ++m) _Pragma("unroll") for (int n = 0; n < 2; ++n) _Pragma("unroll") for (int k = 0; k < 2; ++k) \
;         acc[ai][bj][m][n] = __builtin_amdgcn_mfma_f32_16x16x32_bf16(Bt[n][k], At[m][k], acc[ai][bj][m][n], 0, 0, 0); __builtin_amdgcn_s_setprio(0); } while (0)
; #define PG8_WAIT_V(n) asm volatile("s_waitcnt vmcnt(" #n ")" ::: "memory")
; #define PG8_WAIT_L(n) asm volatile("s_waitcnt lgkmcnt(" #n ")" ::: "memory")
; #define PG8_BAR __builtin_amdgcn_s_barrier()
; #define PG8_SCHED __builtin_amdgcn_sched_barrier(0)
; template <class Sched, class Epi, bool ALIGN_EPI, bool SP2>
; __device__ __forceinline__ void gemm_phase(LAS unsigned char* lds, const int K, const int lda, const int ldb, const Sched& S, const Epi& E) {
;     ...
;         for (int t = 0; t < nt; t += 2) {
;             const bool last = (t == nt - 2);
;             const char* a1 = cA + (size_t)(t + 1) * kstep;
;             const char* a2 = last ? nA : cA + (size_t)(t + 2) * kstep; const char* b2 = last ? nB : cB + (size_t)(t + 2) * kstep;
;             const char* a3 = a2 + kstep; const char* b3 = b2 + kstep;
;     ...
;             PG8_LDA(At, 1, 1); PG8_STAGE(PG8_SB(1, 0), b3, voffB); PG8_STAGE(PG8_SB(1, 1), b3 + hstepB, voffB); PG8_STAGE(PG8_SA(1, 0), a3, voffA);
;             PG8_WAIT_V(8); PG8_WAIT_L(0); PG8_BAR; PG8_MMA(1, 0, At, B0); PG8_MMA(1, 1, At, B1); PG8_BAR; PG8_SCHED;
	s_add_i32 s24, s78, s2
	v_lshl_add_u64 v[174:175], v[174:175], 0, s[4:5]
	s_mov_b32 m0, s24
	ds_read_b128 v[184:187], v149 offset:49152
	ds_read_b128 v[188:191], v149 offset:50176
	ds_read_b128 v[192:195], v149 offset:51200
	ds_read_b128 v[196:199], v149 offset:52224
	ds_read_b128 v[200:203], v149 offset:53248
	ds_read_b128 v[204:207], v149 offset:54272
	ds_read_b128 v[208:211], v149 offset:55296
	ds_read_b128 v[212:215], v149 offset:56320
	global_load_lds_dwordx4 v[174:175], off
	s_add_i32 m0, s24, 0x2000
	s_add_u32 s22, s22, 0x80080
	v_lshl_add_u64 v[174:175], v[216:217], 0, s[4:5]
	s_addc_u32 s23, s23, 0
	s_add_i32 s24, s79, s2
	global_load_lds_dwordx4 v[174:175], off
	v_lshl_add_u64 v[174:175], s[22:23], 0, v[130:131]
	s_mov_b32 m0, s24
	s_nop 0
	global_load_lds_dwordx4 v[174:175], off
	v_lshl_add_u64 v[174:175], s[22:23], 0, v[134:135]
	s_add_i32 m0, s24, 0x2000
	s_nop 0
	global_load_lds_dwordx4 v[174:175], off
	v_lshl_add_u64 v[174:175], v[218:219], 0, s[4:5]
	s_mov_b32 m0, s29
	s_nop 0
	global_load_lds_dwordx4 v[174:175], off
	v_lshl_add_u64 v[174:175], v[220:221], 0, s[4:5]
	s_mov_b32 m0, s33
	s_nop 0
	global_load_lds_dwordx4 v[174:175], off
	s_waitcnt vmcnt(8)
	s_waitcnt lgkmcnt(0)
	s_barrier
	s_setprio 1
	s_waitcnt lgkmcnt(0)
	v_mfma_f32_16x16x32_bf16 v[60:63], v[140:143], v[184:187], v[60:63]
	v_mfma_f32_16x16x32_bf16 v[56:59], v[154:157], v[184:187], v[56:59]
	v_mfma_f32_16x16x32_bf16 v[44:47], v[140:143], v[192:195], v[44:47]
	v_mfma_f32_16x16x32_bf16 v[40:43], v[154:157], v[192:195], v[40:43]
	v_mfma_f32_16x16x32_bf16 v[28:31], v[140:143], v[200:203], v[28:31]
	v_mfma_f32_16x16x32_bf16 v[24:27], v[154:157], v[200:203], v[24:27]
	v_mfma_f32_16x16x32_bf16 v[12:15], v[140:143], v[208:211], v[12:15]
	v_mfma_f32_16x16x32_bf16 v[8:11], v[154:157], v[208:211], v[8:11]
	v_mfma_f32_16x16x32_bf16 v[60:63], v[150:153], v[188:191], v[60:63]
	v_mfma_f32_16x16x32_bf16 v[56:59], v[158:161], v[188:191], v[56:59]
	v_mfma_f32_16x16x32_bf16 v[44:47], v[150:153], v[196:199], v[44:47]
	v_mfma_f32_16x16x32_bf16 v[40:43], v[158:161], v[196:199], v[40:43]
	v_mfma_f32_16x16x32_bf16 v[28:31], v[150:153], v[204:207], v[28:31]
	v_mfma_f32_16x16x32_bf16 v[24:27], v[158:161], v[204:207], v[24:27]
	v_mfma_f32_16x16x32_bf16 v[12:15], v[150:153], v[212:215], v[12:15]
	v_mfma_f32_16x16x32_bf16 v[8:11], v[158:161], v[212:215], v[8:11]
	s_setprio 0
	s_setprio 1
	v_mfma_f32_16x16x32_bf16 v[52:55], v[162:165], v[184:187], v[52:55]
	v_mfma_f32_16x16x32_bf16 v[48:51], v[170:173], v[184:187], v[48:51]
	v_mfma_f32_16x16x32_bf16 v[36:39], v[162:165], v[192:195], v[36:39]
	v_mfma_f32_16x16x32_bf16 v[32:35], v[170:173], v[192:195], v[32:35]
	v_mfma_f32_16x16x32_bf16 v[20:23], v[162:165], v[200:203], v[20:23]
	v_mfma_f32_16x16x32_bf16 v[16:19], v[170:173], v[200:203], v[16:19]
	v_mfma_f32_16x16x32_bf16 v[4:7], v[162:165], v[208:211], v[4:7]
	v_mfma_f32_16x16x32_bf16 v[0:3], v[170:173], v[208:211], v[0:3]
	v_mfma_f32_16x16x32_bf16 v[52:55], v[166:169], v[188:191], v[52:55]
	v_mfma_f32_16x16x32_bf16 v[48:51], v[180:183], v[188:191], v[48:51]
	v_mfma_f32_16x16x32_bf16 v[36:39], v[166:169], v[196:199], v[36:39]
	v_mfma_f32_16x16x32_bf16 v[32:35], v[180:183], v[196:199], v[32:35]
	v_mfma_f32_16x16x32_bf16 v[20:23], v[166:169], v[204:207], v[20:23]
	v_mfma_f32_16x16x32_bf16 v[16:19], v[180:183], v[204:207], v[16:19]
	v_mfma_f32_16x16x32_bf16 v[4:7], v[166:169], v[212:215], v[4:7]
	v_mfma_f32_16x16x32_bf16 v[0:3], v[180:183], v[212:215], v[0:3]
	s_setprio 0
	s_add_i32 s75, s75, 2
	s_add_u32 s20, s20, 0x100
	s_addc_u32 s21, s21, 0
	s_add_u32 s13, s13, 0x100
	s_addc_u32 s74, s74, 0
	s_cmp_gt_u32 s75, 29
	s_barrier
	s_cbranch_scc0 .LBB0_155
	s_and_b64 vcc, exec, s[6:7]
	s_cbranch_vccz .LBB0_158
	s_barrier

; #define PG8_STAGE(bufoff, gbase, voff) do { _Pragma("unroll") for (int _i = 0; _i < 2; ++_i) \
;         __builtin_amdgcn_global_load_lds((const unsigned*)((const char*)(gbase) + (voff)[_i]), (LAS unsigned*)(lds + (bufoff) + ldsw + _i * 8192), 16, 0, 0); } while (0)
; #define PG8_LDA(dst, b, h) do { _Pragma("unroll") for (int m = 0; m < 4; ++m) _Pragma("unroll") for (int k = 0; k < 2; ++k) dst[m][k] = *(const LAS bf16x8*)(lds + PG8_SA(b, h) + aoff + m * 2048 + k * 1024); } while (0)
; #define PG8_LDB(dst, b, h) do { _Pragma("unroll") for (int n = 0; n < 2; ++n) _Pragma("unroll") for (int k = 0; k < 2; ++k) dst[n][k] = *(const LAS bf16x8*)(lds + PG8_SB(b, h) + boff + n * 2048 + k * 1024); } while (0)
; #define PG8_MMA(ai, bj, At, Bt) do { __builtin_amdgcn_s_setprio(1); _Pragma("unroll") for (int m = 0; m < 4; ++m) _Pragma("unroll") for (int n = 0; n < 2; ++n) _Pragma("unroll") for (int k = 0; k < 2; ++k) \
;         acc[ai][bj][m][n] = __builtin_amdgcn_mfma_f32_16x16x32_bf16(Bt[n][k], At[m][k], acc[ai][bj][m][n], 0, 0, 0); __builtin_amdgcn_s_setprio(0); } while (0)
; #define PG8_WAIT_V(n) asm volatile("s_waitcnt vmcnt(" #n ")" ::: "memory")
; #define PG8_WAIT_L(n) asm volatile("s_waitcnt lgkmcnt(" #n ")" ::: "memory")
; #define PG8_BAR __builtin_amdgcn_s_barrier()
; template <class Sched, class Epi, bool ALIGN_EPI, bool SP2>
; __device__ __forceinline__ void gemm_phase(LAS unsigned char* lds, const int K, const int lda, const int ldb, const Sched& S, const Epi& E) {
;     ...
;         for (int t = 0; t < nt; t += 2) {
;             const bool last = (t == nt - 2);
;             const char* a1 = cA + (size_t)(t + 1) * kstep;
;             const char* a2 = last ? nA : cA + (size_t)(t + 2) * kstep; const char* b2 = last ? nB : cB + (size_t)(t + 2) * kstep;
;             const char* a3 = a2 + kstep; const char* b3 = b2 + kstep;
;             if constexpr (SP2) {
;             PG8_LDB(B0, 0, 0); PG8_LDB(B1, 0, 1); PG8_SCHED; PG8_LDA(At, 0, 0); PG8_STAGE(PG8_SA(1, 1), a1 + hstepA, voffA);
;             PG8_WAIT_V(8); PG8_WAIT_L(0); PG8_BAR; PG8_MMA(0, 0, At, B0); PG8_MMA(0, 1, At, B1); PG8_BAR; PG8_SCHED;
;             PG8_LDA(At, 0, 1); PG8_STAGE(PG8_SB(0, 0), b2, voffB); PG8_STAGE(PG8_SB(0, 1), b2 + hstepB, voffB); PG8_STAGE(PG8_SA(0, 0), a2, voffA);
;             PG8_WAIT_V(8); PG8_WAIT_L(0); PG8_BAR; PG8_MMA(1, 0, At, B0); PG8_MMA(1, 1, At, B1); PG8_BAR; PG8_SCHED;
.LBB0_243:
	ds_read_b128 v[124:127], v169
	ds_read_b128 v[132:135], v169 offset:1024
	ds_read_b128 v[136:139], v169 offset:2048
	ds_read_b128 v[140:143], v169 offset:3072
	ds_read_b128 v[144:147], v170
	ds_read_b128 v[156:159], v170 offset:1024
	ds_read_b128 v[160:163], v170 offset:2048
	ds_read_b128 v[182:185], v170 offset:3072
	s_add_u32 s22, s20, 0x100
	s_addc_u32 s23, s21, 0
	s_cmpk_eq_i32 s91, 0x54
	s_cselect_b32 s27, s17, s23
	s_cselect_b32 s26, s16, s22
	s_cselect_b32 s25, s19, s90
	s_cselect_b32 s24, s18, s89
	s_mov_b32 m0, s78
	v_lshl_add_u64 v[164:165], s[20:21], 0, v[152:153]
	ds_read_b128 v[186:189], v171
	ds_read_b128 v[190:193], v171 offset:1024
	ds_read_b128 v[194:197], v171 offset:2048
	ds_read_b128 v[198:201], v171 offset:3072
	ds_read_b128 v[202:205], v171 offset:4096
	ds_read_b128 v[206:209], v171 offset:5120
	ds_read_b128 v[210:213], v171 offset:6144
	ds_read_b128 v[214:217], v171 offset:7168
	global_load_lds_dwordx4 v[164:165], off
	v_lshl_add_u64 v[164:165], s[20:21], 0, v[154:155]
	s_mov_b32 m0, s79
	s_nop 0
	global_load_lds_dwordx4 v[164:165], off
	s_waitcnt vmcnt(8)
	s_waitcnt lgkmcnt(0)
	s_barrier
	s_setprio 1
	s_waitcnt lgkmcnt(0)
	v_mfma_f32_16x16x32_bf16 v[128:131], v[124:127], v[186:189], v[128:131]
	v_mfma_f32_16x16x32_bf16 v[120:123], v[136:139], v[186:189], v[120:123]
	v_mfma_f32_16x16x32_bf16 v[108:111], v[124:127], v[194:197], v[108:111]
	v_mfma_f32_16x16x32_bf16 v[104:107], v[136:139], v[194:197], v[104:107]
	v_mfma_f32_16x16x32_bf16 v[92:95], v[124:127], v[202:205], v[92:95]
	v_mfma_f32_16x16x32_bf16 v[88:91], v[136:139], v[202:205], v[88:91]
	v_mfma_f32_16x16x32_bf16 v[76:79], v[124:127], v[210:213], v[76:79]
	v_mfma_f32_16x16x32_bf16 v[72:75], v[136:139], v[210:213], v[72:75]
	v_mfma_f32_16x16x32_bf16 v[128:131], v[132:135], v[190:193], v[128:131]
	v_mfma_f32_16x16x32_bf16 v[120:123], v[140:143], v[190:193], v[120:123]
	v_mfma_f32_16x16x32_bf16 v[108:111], v[132:135], v[198:201], v[108:111]
	v_mfma_f32_16x16x32_bf16 v[104:107], v[140:143], v[198:201], v[104:107]
	v_mfma_f32_16x16x32_bf16 v[92:95], v[132:135], v[206:209], v[92:95]
	v_mfma_f32_16x16x32_bf16 v[88:91], v[140:143], v[206:209], v[88:91]
	v_mfma_f32_16x16x32_bf16 v[76:79], v[132:135], v[214:217], v[76:79]
	v_mfma_f32_16x16x32_bf16 v[72:75], v[140:143], v[214:217], v[72:75]
	s_setprio 0
	s_setprio 1
	v_mfma_f32_16x16x32_bf16 v[116:119], v[144:147], v[186:189], v[116:119]
	v_mfma_f32_16x16x32_bf16 v[112:115], v[160:163], v[186:189], v[112:115]
	v_mfma_f32_16x16x32_bf16 v[100:103], v[144:147], v[194:197], v[100:103]
	v_mfma_f32_16x16x32_bf16 v[96:99], v[160:163], v[194:197], v[96:99]
	v_mfma_f32_16x16x32_bf16 v[84:87], v[144:147], v[202:205], v[84:87]
	v_mfma_f32_16x16x32_bf16 v[80:83], v[160:163], v[202:205], v[80:83]
	v_mfma_f32_16x16x32_bf16 v[68:71], v[144:147], v[210:213], v[68:71]
	v_mfma_f32_16x16x32_bf16 v[64:67], v[160:163], v[210:213], v[64:67]
	v_mfma_f32_16x16x32_bf16 v[116:119], v[156:159], v[190:193], v[116:119]
	v_mfma_f32_16x16x32_bf16 v[112:115], v[182:185], v[190:193], v[112:115]
	v_mfma_f32_16x16x32_bf16 v[100:103], v[156:159], v[198:201], v[100:103]
	v_mfma_f32_16x16x32_bf16 v[96:99], v[182:185], v[198:201], v[96:99]
	v_mfma_f32_16x16x32_bf16 v[84:87], v[156:159], v[206:209], v[84:87]
	v_mfma_f32_16x16x32_bf16 v[80:83], v[182:185], v[206:209], v[80:83]
	v_mfma_f32_16x16x32_bf16 v[68:71], v[156:159], v[214:217], v[68:71]
	v_mfma_f32_16x16x32_bf16 v[64:67], v[182:185], v[214:217], v[64:67]
	s_setprio 0
	s_barrier
	s_mov_b32 m0, s84
	v_lshl_add_u64 v[164:165], s[24:25], 0, v[148:149]
	ds_read_b128 v[186:189], v171 offset:16384
	ds_read_b128 v[190:193], v171 offset:17408
	ds_read_b128 v[194:197], v171 offset:18432
	ds_read_b128 v[198:201], v171 offset:19456
	ds_read_b128 v[202:205], v171 offset:20480
	ds_read_b128 v[206:209], v171 offset:21504
	ds_read_b128 v[210:213], v171 offset:22528
	ds_read_b128 v[214:217], v171 offset:23552
	global_load_lds_dwordx4 v[164:165], off
	s_add_i32 m0, s84, 0x2000
	s_add_u32 s20, s24, 0x160000
	v_lshl_add_u64 v[174:175], s[24:25], 0, v[150:151]
	s_addc_u32 s21, s25, 0
	s_add_i32 s96, s53, s13
	global_load_lds_dwordx4 v[174:175], off
	v_lshl_add_u64 v[218:219], s[20:21], 0, v[148:149]
	s_mov_b32 m0, s96
	v_lshl_add_u64 v[220:221], s[26:27], 0, v[150:151]
	global_load_lds_dwordx4 v[218:219], off
	v_lshl_add_u64 v[218:219], s[20:21], 0, v[150:151]
	s_add_i32 m0, s96, 0x2000
	s_nop 0
	global_load_lds_dwordx4 v[218:219], off
	v_lshl_add_u64 v[218:219], s[26:27], 0, v[148:149]
	s_mov_b32 m0, s28
	s_nop 0
	global_load_lds_dwordx4 v[218:219], off
	s_mov_b32 m0, s29
	s_nop 0
	global_load_lds_dwordx4 v[220:221], off
	s_waitcnt vmcnt(8)
	s_waitcnt lgkmcnt(0)
	s_barrier
; #define PG8_STAGE(bufoff, gbase, voff) do { _Pragma("unroll") for (int _i = 0; _i < 2; ++_i) \
;         __builtin_amdgcn_global_load_lds((const unsigned*)((const char*)(gbase) + (voff)[_i]), (LAS unsigned*)(lds + (bufoff) + ldsw + _i * 8192), 16, 0, 0); } while (0)
; #define PG8_LDA(dst, b, h) do { _Pragma("unroll") for (int m = 0; m < 4; ++m) _Pragma("unroll") for (int k = 0; k < 2; ++k) dst[m][k] = *(const LAS bf16x8*)(lds + PG8_SA(b, h) + aoff + m * 2048 + k * 1024); } while (0)
; #define PG8_LDB(dst, b, h) do { _Pragma("unroll") for (int n = 0; n < 2; ++n) _Pragma("unroll") for (int k = 0; k < 2; ++k) dst[n][k] = *(const LAS bf16x8*)(lds + PG8_SB(b, h) + boff + n * 2048 + k * 1024); } while (0)
; #define PG8_MMA(ai, bj, At, Bt) do { __builtin_amdgcn_s_setprio(1); _Pragma("unroll") for (int m = 0; m < 4; ++m) _Pragma("unroll") for (int n = 0; n < 2; ++n) _Pragma("unroll") for (int k = 0; k < 2; ++k) \
;         acc[ai][bj][m][n] = __builtin_amdgcn_mfma_f32_16x16x32_bf16(Bt[n][k], At[m][k], acc[ai][bj][m][n], 0, 0, 0); __builtin_amdgcn_s_setprio(0); } while (0)
; #define PG8_WAIT_V(n) asm volatile("s_waitcnt vmcnt(" #n ")" ::: "memory")
; #define PG8_WAIT_L(n) asm volatile("s_waitcnt lgkmcnt(" #n ")" ::: "memory")
; #define PG8_BAR __builtin_amdgcn_s_barrier()
; #define PG8_SCHED __builtin_amdgcn_sched_barrier(0)
; template <class Sched, class Epi, bool ALIGN_EPI, bool SP2>
; __device__ __forceinline__ void gemm_phase(LAS unsigned char* lds, const int K, const int lda, const int ldb, const Sched& S, const Epi& E) {
;     ...
;             PG8_WAIT_V(8); PG8_WAIT_L(0); PG8_BAR; PG8_MMA(1, 0, At, B0); PG8_MMA(1, 1, At, B1); PG8_BAR; PG8_SCHED;
;             PG8_LDB(B0, 1, 0); PG8_LDB(B1, 1, 1); PG8_SCHED; PG8_LDA(At, 1, 0); PG8_STAGE(PG8_SA(0, 1), a2 + hstepA, voffA);
;             PG8_WAIT_V(8); PG8_WAIT_L(0); PG8_BAR; PG8_MMA(0, 0, At, B0); PG8_MMA(0, 1, At, B1); PG8_BAR; PG8_SCHED;
;             PG8_LDA(At, 1, 1); PG8_STAGE(PG8_SB(1, 0), b3, voffB); PG8_STAGE(PG8_SB(1, 1), b3 + hstepB, voffB); PG8_STAGE(PG8_SA(1, 0), a3, voffA);
;             PG8_WAIT_V(8); PG8_WAIT_L(0); PG8_BAR; PG8_MMA(1, 0, At, B0); PG8_MMA(1, 1, At, B1); PG8_BAR; PG8_SCHED;
	s_setprio 1
	s_waitcnt lgkmcnt(0)
	v_mfma_f32_16x16x32_bf16 v[60:63], v[124:127], v[186:189], v[60:63]
	v_mfma_f32_16x16x32_bf16 v[56:59], v[136:139], v[186:189], v[56:59]
	v_mfma_f32_16x16x32_bf16 v[44:47], v[124:127], v[194:197], v[44:47]
	v_mfma_f32_16x16x32_bf16 v[40:43], v[136:139], v[194:197], v[40:43]
	v_mfma_f32_16x16x32_bf16 v[28:31], v[124:127], v[202:205], v[28:31]
	v_mfma_f32_16x16x32_bf16 v[24:27], v[136:139], v[202:205], v[24:27]
	v_mfma_f32_16x16x32_bf16 v[12:15], v[124:127], v[210:213], v[12:15]
	v_mfma_f32_16x16x32_bf16 v[8:11], v[136:139], v[210:213], v[8:11]
	v_mfma_f32_16x16x32_bf16 v[60:63], v[132:135], v[190:193], v[60:63]
	v_mfma_f32_16x16x32_bf16 v[56:59], v[140:143], v[190:193], v[56:59]
	v_mfma_f32_16x16x32_bf16 v[44:47], v[132:135], v[198:201], v[44:47]
	v_mfma_f32_16x16x32_bf16 v[40:43], v[140:143], v[198:201], v[40:43]
	v_mfma_f32_16x16x32_bf16 v[28:31], v[132:135], v[206:209], v[28:31]
	v_mfma_f32_16x16x32_bf16 v[24:27], v[140:143], v[206:209], v[24:27]
	v_mfma_f32_16x16x32_bf16 v[12:15], v[132:135], v[214:217], v[12:15]
	v_mfma_f32_16x16x32_bf16 v[8:11], v[140:143], v[214:217], v[8:11]
	s_setprio 0
	s_setprio 1
	v_mfma_f32_16x16x32_bf16 v[52:55], v[144:147], v[186:189], v[52:55]
	v_mfma_f32_16x16x32_bf16 v[48:51], v[160:163], v[186:189], v[48:51]
	v_mfma_f32_16x16x32_bf16 v[36:39], v[144:147], v[194:197], v[36:39]
	v_mfma_f32_16x16x32_bf16 v[32:35], v[160:163], v[194:197], v[32:35]
	v_mfma_f32_16x16x32_bf16 v[20:23], v[144:147], v[202:205], v[20:23]
	v_mfma_f32_16x16x32_bf16 v[16:19], v[160:163], v[202:205], v[16:19]
	v_mfma_f32_16x16x32_bf16 v[4:7], v[144:147], v[210:213], v[4:7]
	v_mfma_f32_16x16x32_bf16 v[0:3], v[160:163], v[210:213], v[0:3]
	v_mfma_f32_16x16x32_bf16 v[52:55], v[156:159], v[190:193], v[52:55]
	v_mfma_f32_16x16x32_bf16 v[48:51], v[182:185], v[190:193], v[48:51]
	v_mfma_f32_16x16x32_bf16 v[36:39], v[156:159], v[198:201], v[36:39]
	v_mfma_f32_16x16x32_bf16 v[32:35], v[182:185], v[198:201], v[32:35]
	v_mfma_f32_16x16x32_bf16 v[20:23], v[156:159], v[206:209], v[20:23]
	v_mfma_f32_16x16x32_bf16 v[16:19], v[182:185], v[206:209], v[16:19]
	v_mfma_f32_16x16x32_bf16 v[4:7], v[156:159], v[214:217], v[4:7]
	v_mfma_f32_16x16x32_bf16 v[0:3], v[182:185], v[214:217], v[0:3]
	s_setprio 0
	s_barrier
	s_add_i32 s96, 0, 0x18000
	s_add_i32 s97, 0, 0x1c000
	v_add_u32_e32 v140, s96, v167
	v_add_u32_e32 v173, s97, v167
	ds_read_b128 v[124:127], v140
	ds_read_b128 v[132:135], v140 offset:1024
	ds_read_b128 v[136:139], v140 offset:2048
	ds_read_b128 v[140:143], v140 offset:3072
	ds_read_b128 v[144:147], v173
	ds_read_b128 v[156:159], v173 offset:1024
	ds_read_b128 v[160:163], v173 offset:2048
	ds_read_b128 v[182:185], v173 offset:3072
	s_add_u32 s20, s26, 0x160000
	s_addc_u32 s21, s27, 0
	s_mov_b32 m0, s33
	v_lshl_add_u64 v[222:223], s[20:21], 0, v[148:149]
	ds_read_b128 v[186:189], v171 offset:32768
	ds_read_b128 v[190:193], v171 offset:33792
	ds_read_b128 v[194:197], v171 offset:34816
	ds_read_b128 v[198:201], v171 offset:35840
	ds_read_b128 v[202:205], v171 offset:36864
	ds_read_b128 v[206:209], v171 offset:37888
	ds_read_b128 v[210:213], v171 offset:38912
	ds_read_b128 v[214:217], v171 offset:39936
	global_load_lds_dwordx4 v[222:223], off
	v_lshl_add_u64 v[222:223], s[20:21], 0, v[150:151]
	s_mov_b32 m0, s35
	s_nop 0
	global_load_lds_dwordx4 v[222:223], off
	s_waitcnt vmcnt(8)
	s_waitcnt lgkmcnt(0)
	s_barrier
	s_setprio 1
	s_waitcnt lgkmcnt(0)
	v_mfma_f32_16x16x32_bf16 v[128:131], v[124:127], v[186:189], v[128:131]
	v_mfma_f32_16x16x32_bf16 v[120:123], v[136:139], v[186:189], v[120:123]
	v_mfma_f32_16x16x32_bf16 v[108:111], v[124:127], v[194:197], v[108:111]
	v_mfma_f32_16x16x32_bf16 v[104:107], v[136:139], v[194:197], v[104:107]
	v_mfma_f32_16x16x32_bf16 v[92:95], v[124:127], v[202:205], v[92:95]
	v_mfma_f32_16x16x32_bf16 v[88:91], v[136:139], v[202:205], v[88:91]
	v_mfma_f32_16x16x32_bf16 v[76:79], v[124:127], v[210:213], v[76:79]
	v_mfma_f32_16x16x32_bf16 v[72:75], v[136:139], v[210:213], v[72:75]
	v_mfma_f32_16x16x32_bf16 v[128:131], v[132:135], v[190:193], v[128:131]
	v_mfma_f32_16x16x32_bf16 v[120:123], v[140:143], v[190:193], v[120:123]
	v_mfma_f32_16x16x32_bf16 v[108:111], v[132:135], v[198:201], v[108:111]
	v_mfma_f32_16x16x32_bf16 v[104:107], v[140:143], v[198:201], v[104:107]
	v_mfma_f32_16x16x32_bf16 v[92:95], v[132:135], v[206:209], v[92:95]
	v_mfma_f32_16x16x32_bf16 v[88:91], v[140:143], v[206:209], v[88:91]
	v_mfma_f32_16x16x32_bf16 v[76:79], v[132:135], v[214:217], v[76:79]
	v_mfma_f32_16x16x32_bf16 v[72:75], v[140:143], v[214:217], v[72:75]
	s_setprio 0
	s_setprio 1
	v_mfma_f32_16x16x32_bf16 v[116:119], v[144:147], v[186:189], v[116:119]
	v_mfma_f32_16x16x32_bf16 v[112:115], v[160:163], v[186:189], v[112:115]
	v_mfma_f32_16x16x32_bf16 v[100:103], v[144:147], v[194:197], v[100:103]
	v_mfma_f32_16x16x32_bf16 v[96:99], v[160:163], v[194:197], v[96:99]
	v_mfma_f32_16x16x32_bf16 v[84:87], v[144:147], v[202:205], v[84:87]
	v_mfma_f32_16x16x32_bf16 v[80:83], v[160:163], v[202:205], v[80:83]
	v_mfma_f32_16x16x32_bf16 v[68:71], v[144:147], v[210:213], v[68:71]
	v_mfma_f32_16x16x32_bf16 v[64:67], v[160:163], v[210:213], v[64:67]
	v_mfma_f32_16x16x32_bf16 v[116:119], v[156:159], v[190:193], v[116:119]
	v_mfma_f32_16x16x32_bf16 v[112:115], v[182:185], v[190:193], v[112:115]
	v_mfma_f32_16x16x32_bf16 v[100:103], v[156:159], v[198:201], v[100:103]
	v_mfma_f32_16x16x32_bf16 v[96:99], v[182:185], v[198:201], v[96:99]
	v_mfma_f32_16x16x32_bf16 v[84:87], v[156:159], v[206:209], v[84:87]
	v_mfma_f32_16x16x32_bf16 v[80:83], v[182:185], v[206:209], v[80:83]
	v_mfma_f32_16x16x32_bf16 v[68:71], v[156:159], v[214:217], v[68:71]
	v_mfma_f32_16x16x32_bf16 v[64:67], v[182:185], v[214:217], v[64:67]
	s_setprio 0
	s_barrier
; #define PG8_STAGE(bufoff, gbase, voff) do { _Pragma("unroll") for (int _i = 0; _i < 2; ++_i) \
;         __builtin_amdgcn_global_load_lds((const unsigned*)((const char*)(gbase) + (voff)[_i]), (LAS unsigned*)(lds + (bufoff) + ldsw + _i * 8192), 16, 0, 0); } while (0)
; #define PG8_LDA(dst, b, h) do { _Pragma("unroll") for (int m = 0; m < 4; ++m) _Pragma("unroll") for (int k = 0; k < 2; ++k) dst[m][k] = *(const LAS bf16x8*)(lds + PG8_SA(b, h) + aoff + m * 2048 + k * 1024); } while (0)
; #define PG8_MMA(ai, bj, At, Bt) do { __builtin_amdgcn_s_setprio(1); _Pragma("unroll") for (int m = 0; m < 4; ++m) _Pragma("unroll") for (int n = 0; n < 2; ++n) _Pragma("unroll") for (int k = 0; k < 2; ++k) \
;         acc[ai][bj][m][n] = __builtin_amdgcn_mfma_f32_16x16x32_bf16(Bt[n][k], At[m][k], acc[ai][bj][m][n], 0, 0, 0); __builtin_amdgcn_s_setprio(0); } while (0)
; #define PG8_WAIT_V(n) asm volatile("s_waitcnt vmcnt(" #n ")" ::: "memory")
; #define PG8_WAIT_L(n) asm volatile("s_waitcnt lgkmcnt(" #n ")" ::: "memory")
; #define PG8_BAR __builtin_amdgcn_s_barrier()
; #define PG8_SCHED __builtin_amdgcn_sched_barrier(0)
; template <class Sched, class Epi, bool ALIGN_EPI, bool SP2>
; __device__ __forceinline__ void gemm_phase(LAS unsigned char* lds, const int K, const int lda, const int ldb, const Sched& S, const Epi& E) {
;     ...
;         for (int t = 0; t < nt; t += 2) {
;             const bool last = (t == nt - 2);
;             const char* a1 = cA + (size_t)(t + 1) * kstep;
;             const char* a2 = last ? nA : cA + (size_t)(t + 2) * kstep; const char* b2 = last ? nB : cB + (size_t)(t + 2) * kstep;
;             const char* a3 = a2 + kstep; const char* b3 = b2 + kstep;
;     ...
;             PG8_LDA(At, 1, 1); PG8_STAGE(PG8_SB(1, 0), b3, voffB); PG8_STAGE(PG8_SB(1, 1), b3 + hstepB, voffB); PG8_STAGE(PG8_SA(1, 0), a3, voffA);
;             PG8_WAIT_V(8); PG8_WAIT_L(0); PG8_BAR; PG8_MMA(1, 0, At, B0); PG8_MMA(1, 1, At, B1); PG8_BAR; PG8_SCHED;
	s_add_i32 s20, s96, s13
	v_lshl_add_u64 v[164:165], v[164:165], 0, s[6:7]
	s_mov_b32 m0, s20
	ds_read_b128 v[186:189], v171 offset:49152
	ds_read_b128 v[190:193], v171 offset:50176
	ds_read_b128 v[194:197], v171 offset:51200
	ds_read_b128 v[198:201], v171 offset:52224
	ds_read_b128 v[202:205], v171 offset:53248
	ds_read_b128 v[206:209], v171 offset:54272
	ds_read_b128 v[210:213], v171 offset:55296
	ds_read_b128 v[214:217], v171 offset:56320
	global_load_lds_dwordx4 v[164:165], off
	s_add_i32 m0, s20, 0x2000
	s_add_u32 s20, s24, 0x160080
	v_lshl_add_u64 v[164:165], v[174:175], 0, s[6:7]
	s_addc_u32 s21, s25, 0
	s_add_i32 s24, s97, s13
	global_load_lds_dwordx4 v[164:165], off
	v_lshl_add_u64 v[164:165], s[20:21], 0, v[148:149]
	s_mov_b32 m0, s24
	s_nop 0
	global_load_lds_dwordx4 v[164:165], off
	v_lshl_add_u64 v[164:165], s[20:21], 0, v[150:151]
	s_add_i32 m0, s24, 0x2000
	s_nop 0
	global_load_lds_dwordx4 v[164:165], off
	v_lshl_add_u64 v[164:165], v[218:219], 0, s[6:7]
	s_mov_b32 m0, s51
	s_nop 0
	global_load_lds_dwordx4 v[164:165], off
	v_lshl_add_u64 v[164:165], v[220:221], 0, s[6:7]
	s_mov_b32 m0, s52
	s_nop 0
	global_load_lds_dwordx4 v[164:165], off
	s_waitcnt vmcnt(8)
	s_waitcnt lgkmcnt(0)
	s_barrier
	s_setprio 1
	s_waitcnt lgkmcnt(0)
	v_mfma_f32_16x16x32_bf16 v[60:63], v[124:127], v[186:189], v[60:63]
	v_mfma_f32_16x16x32_bf16 v[56:59], v[136:139], v[186:189], v[56:59]
	v_mfma_f32_16x16x32_bf16 v[44:47], v[124:127], v[194:197], v[44:47]
	v_mfma_f32_16x16x32_bf16 v[40:43], v[136:139], v[194:197], v[40:43]
	v_mfma_f32_16x16x32_bf16 v[28:31], v[124:127], v[202:205], v[28:31]
	v_mfma_f32_16x16x32_bf16 v[24:27], v[136:139], v[202:205], v[24:27]
	v_mfma_f32_16x16x32_bf16 v[12:15], v[124:127], v[210:213], v[12:15]
	v_mfma_f32_16x16x32_bf16 v[8:11], v[136:139], v[210:213], v[8:11]
	v_mfma_f32_16x16x32_bf16 v[60:63], v[132:135], v[190:193], v[60:63]
	v_mfma_f32_16x16x32_bf16 v[56:59], v[140:143], v[190:193], v[56:59]
	v_mfma_f32_16x16x32_bf16 v[44:47], v[132:135], v[198:201], v[44:47]
	v_mfma_f32_16x16x32_bf16 v[40:43], v[140:143], v[198:201], v[40:43]
	v_mfma_f32_16x16x32_bf16 v[28:31], v[132:135], v[206:209], v[28:31]
	v_mfma_f32_16x16x32_bf16 v[24:27], v[140:143], v[206:209], v[24:27]
	v_mfma_f32_16x16x32_bf16 v[12:15], v[132:135], v[214:217], v[12:15]
	v_mfma_f32_16x16x32_bf16 v[8:11], v[140:143], v[214:217], v[8:11]
	s_setprio 0
	s_setprio 1
	v_mfma_f32_16x16x32_bf16 v[52:55], v[144:147], v[186:189], v[52:55]
	v_mfma_f32_16x16x32_bf16 v[48:51], v[160:163], v[186:189], v[48:51]
	v_mfma_f32_16x16x32_bf16 v[36:39], v[144:147], v[194:197], v[36:39]
	v_mfma_f32_16x16x32_bf16 v[32:35], v[160:163], v[194:197], v[32:35]
	v_mfma_f32_16x16x32_bf16 v[20:23], v[144:147], v[202:205], v[20:23]
	v_mfma_f32_16x16x32_bf16 v[16:19], v[160:163], v[202:205], v[16:19]
	v_mfma_f32_16x16x32_bf16 v[4:7], v[144:147], v[210:213], v[4:7]
	v_mfma_f32_16x16x32_bf16 v[0:3], v[160:163], v[210:213], v[0:3]
	v_mfma_f32_16x16x32_bf16 v[52:55], v[156:159], v[190:193], v[52:55]
	v_mfma_f32_16x16x32_bf16 v[48:51], v[182:185], v[190:193], v[48:51]
	v_mfma_f32_16x16x32_bf16 v[36:39], v[156:159], v[198:201], v[36:39]
	v_mfma_f32_16x16x32_bf16 v[32:35], v[182:185], v[198:201], v[32:35]
	v_mfma_f32_16x16x32_bf16 v[20:23], v[156:159], v[206:209], v[20:23]
	v_mfma_f32_16x16x32_bf16 v[16:19], v[182:185], v[206:209], v[16:19]
	v_mfma_f32_16x16x32_bf16 v[4:7], v[156:159], v[214:217], v[4:7]
	v_mfma_f32_16x16x32_bf16 v[0:3], v[182:185], v[214:217], v[0:3]
	s_setprio 0
	s_add_i32 s91, s91, 2
	s_add_u32 s89, s89, 0x100
	s_addc_u32 s90, s90, 0
	s_cmpk_gt_u32 s91, 0x55
	s_mov_b64 s[20:21], s[22:23]
	s_barrier
	s_cbranch_scc0 .LBB0_243
	s_and_b64 vcc, exec, s[10:11]
	s_cbranch_vccz .LBB0_246
	s_barrier

; #define PG8_STAGE(bufoff, gbase, voff) do { _Pragma("unroll") for (int _i = 0; _i < 2; ++_i) \
;         __builtin_amdgcn_global_load_lds((const unsigned*)((const char*)(gbase) + (voff)[_i]), (LAS unsigned*)(lds + (bufoff) + ldsw + _i * 8192), 16, 0, 0); } while (0)
; #define PG8_LDA(dst, b, h) do { _Pragma("unroll") for (int m = 0; m < 4; ++m) _Pragma("unroll") for (int k = 0; k < 2; ++k) dst[m][k] = *(const LAS bf16x8*)(lds + PG8_SA(b, h) + aoff + m * 2048 + k * 1024); } while (0)
; #define PG8_LDB(dst, b, h) do { _Pragma("unroll") for (int n = 0; n < 2; ++n) _Pragma("unroll") for (int k = 0; k < 2; ++k) dst[n][k] = *(const LAS bf16x8*)(lds + PG8_SB(b, h) + boff + n * 2048 + k * 1024); } while (0)
; #define PG8_MMA(ai, bj, At, Bt) do { __builtin_amdgcn_s_setprio(1); _Pragma("unroll") for (int m = 0; m < 4; ++m) _Pragma("unroll") for (int n = 0; n < 2; ++n) _Pragma("unroll") for (int k = 0; k < 2; ++k) \
;         acc[ai][bj][m][n] = __builtin_amdgcn_mfma_f32_16x16x32_bf16(Bt[n][k], At[m][k], acc[ai][bj][m][n], 0, 0, 0); __builtin_amdgcn_s_setprio(0); } while (0)
; #define PG8_WAIT_V(n) asm volatile("s_waitcnt vmcnt(" #n ")" ::: "memory")
; #define PG8_WAIT_L(n) asm volatile("s_waitcnt lgkmcnt(" #n ")" ::: "memory")
; #define PG8_BAR __builtin_amdgcn_s_barrier()
; template <class Sched, class Epi, bool ALIGN_EPI, bool SP2>
; __device__ __forceinline__ void gemm_phase(LAS unsigned char* lds, const int K, const int lda, const int ldb, const Sched& S, const Epi& E) {
;     ...
;         for (int t = 0; t < nt; t += 2) {
;             const bool last = (t == nt - 2);
;             const char* a1 = cA + (size_t)(t + 1) * kstep;
;             const char* a2 = last ? nA : cA + (size_t)(t + 2) * kstep; const char* b2 = last ? nB : cB + (size_t)(t + 2) * kstep;
;             const char* a3 = a2 + kstep; const char* b3 = b2 + kstep;
;             if constexpr (SP2) {
;             PG8_LDB(B0, 0, 0); PG8_LDB(B1, 0, 1); PG8_SCHED; PG8_LDA(At, 0, 0); PG8_STAGE(PG8_SA(1, 1), a1 + hstepA, voffA);
;             PG8_WAIT_V(8); PG8_WAIT_L(0); PG8_BAR; PG8_MMA(0, 0, At, B0); PG8_MMA(0, 1, At, B1); PG8_BAR; PG8_SCHED;
;             PG8_LDA(At, 0, 1); PG8_STAGE(PG8_SB(0, 0), b2, voffB); PG8_STAGE(PG8_SB(0, 1), b2 + hstepB, voffB); PG8_STAGE(PG8_SA(0, 0), a2, voffA);
;             PG8_WAIT_V(8); PG8_WAIT_L(0); PG8_BAR; PG8_MMA(1, 0, At, B0); PG8_MMA(1, 1, At, B1); PG8_BAR; PG8_SCHED;
.LBB0_353:
	s_waitcnt lgkmcnt(0)
	ds_read_b128 v[32:35], v211
	ds_read_b128 v[36:39], v211 offset:1024
	ds_read_b128 v[48:51], v211 offset:2048
	ds_read_b128 v[52:55], v211 offset:3072
	ds_read_b128 v[56:59], v212
	ds_read_b128 v[60:63], v212 offset:1024
	ds_read_b128 v[64:67], v212 offset:2048
	ds_read_b128 v[68:71], v212 offset:3072
	s_add_u32 s8, s26, 0xfff80080
	s_addc_u32 s9, s27, -1
	s_cmp_eq_u32 s7, 28
	s_cselect_b32 s37, s1, s9
	s_cselect_b32 s36, s4, s8
	s_cselect_b32 s29, s21, s6
	s_cselect_b32 s28, vcc_lo, vcc_hi
	v_lshl_add_u64 v[208:209], s[26:27], 0, v[192:193]
	s_add_i32 m0, s89, 0xc000
	ds_read_b128 v[76:79], v213
	ds_read_b128 v[80:83], v213 offset:1024
	ds_read_b128 v[88:91], v213 offset:2048
	ds_read_b128 v[92:95], v213 offset:3072
	ds_read_b128 v[196:199], v213 offset:4096
	ds_read_b128 v[200:203], v213 offset:5120
	ds_read_b128 v[204:207], v213 offset:6144
	ds_read_b128 v[216:219], v213 offset:7168
	global_load_lds_dwordx4 v[208:209], off
	v_lshl_add_u64 v[208:209], s[26:27], 0, v[194:195]
	s_add_i32 m0, s89, 0xe000
	s_nop 0
	global_load_lds_dwordx4 v[208:209], off
	s_waitcnt vmcnt(8)
	s_waitcnt lgkmcnt(0)
	s_barrier
	s_setprio 1
	s_waitcnt lgkmcnt(0)
	v_mfma_f32_16x16x32_bf16 v[172:175], v[32:35], v[76:79], v[172:175]
	v_mfma_f32_16x16x32_bf16 v[168:171], v[48:51], v[76:79], v[168:171]
	v_mfma_f32_16x16x32_bf16 v[156:159], v[32:35], v[88:91], v[156:159]
	v_mfma_f32_16x16x32_bf16 v[152:155], v[48:51], v[88:91], v[152:155]
	v_mfma_f32_16x16x32_bf16 v[140:143], v[32:35], v[196:199], v[140:143]
	v_mfma_f32_16x16x32_bf16 v[136:139], v[48:51], v[196:199], v[136:139]
	v_mfma_f32_16x16x32_bf16 v[124:127], v[32:35], v[204:207], v[124:127]
	v_mfma_f32_16x16x32_bf16 v[120:123], v[48:51], v[204:207], v[120:123]
	v_mfma_f32_16x16x32_bf16 v[172:175], v[36:39], v[80:83], v[172:175]
	v_mfma_f32_16x16x32_bf16 v[168:171], v[52:55], v[80:83], v[168:171]
	v_mfma_f32_16x16x32_bf16 v[156:159], v[36:39], v[92:95], v[156:159]
	v_mfma_f32_16x16x32_bf16 v[152:155], v[52:55], v[92:95], v[152:155]
	v_mfma_f32_16x16x32_bf16 v[140:143], v[36:39], v[200:203], v[140:143]
	v_mfma_f32_16x16x32_bf16 v[136:139], v[52:55], v[200:203], v[136:139]
	v_mfma_f32_16x16x32_bf16 v[124:127], v[36:39], v[216:219], v[124:127]
	v_mfma_f32_16x16x32_bf16 v[120:123], v[52:55], v[216:219], v[120:123]
	s_setprio 0
	s_setprio 1
	v_mfma_f32_16x16x32_bf16 v[164:167], v[56:59], v[76:79], v[164:167]
	v_mfma_f32_16x16x32_bf16 v[76:79], v[64:67], v[76:79], v[160:163]
	v_mfma_f32_16x16x32_bf16 v[164:167], v[60:63], v[80:83], v[164:167]
	v_mfma_f32_16x16x32_bf16 v[76:79], v[68:71], v[80:83], v[76:79]
	v_mfma_f32_16x16x32_bf16 v[80:83], v[56:59], v[88:91], v[148:151]
	v_mfma_f32_16x16x32_bf16 v[88:91], v[64:67], v[88:91], v[144:147]
	v_mfma_f32_16x16x32_bf16 v[128:131], v[64:67], v[196:199], v[128:131]
	v_mfma_f32_16x16x32_bf16 v[116:119], v[56:59], v[204:207], v[116:119]
	v_mfma_f32_16x16x32_bf16 v[112:115], v[64:67], v[204:207], v[112:115]
	v_mfma_f32_16x16x32_bf16 v[80:83], v[60:63], v[92:95], v[80:83]
	v_mfma_f32_16x16x32_bf16 v[88:91], v[68:71], v[92:95], v[88:91]
	v_mfma_f32_16x16x32_bf16 v[92:95], v[56:59], v[196:199], v[132:135]
	v_mfma_f32_16x16x32_bf16 v[128:131], v[68:71], v[200:203], v[128:131]
	v_mfma_f32_16x16x32_bf16 v[116:119], v[60:63], v[216:219], v[116:119]
	v_mfma_f32_16x16x32_bf16 v[112:115], v[68:71], v[216:219], v[112:115]
	v_mfma_f32_16x16x32_bf16 v[92:95], v[60:63], v[200:203], v[92:95]
	s_setprio 0
	s_barrier
	s_add_i32 s8, s85, s88
	v_lshl_add_u64 v[208:209], s[28:29], 0, v[186:187]
	s_mov_b32 m0, s8
	ds_read_b128 v[132:135], v213 offset:16384
	ds_read_b128 v[144:147], v213 offset:17408
	ds_read_b128 v[148:151], v213 offset:18432
	ds_read_b128 v[160:163], v213 offset:19456
	ds_read_b128 v[196:199], v213 offset:20480
	ds_read_b128 v[200:203], v213 offset:21504
	ds_read_b128 v[204:207], v213 offset:22528
	ds_read_b128 v[216:219], v213 offset:23552
	global_load_lds_dwordx4 v[208:209], off
	s_add_i32 m0, s8, 0x2000
	s_add_u32 s8, s28, 0x80000
	v_lshl_add_u64 v[228:229], s[28:29], 0, v[190:191]
	s_addc_u32 s9, s29, 0
	s_add_i32 s51, s50, s88
	global_load_lds_dwordx4 v[228:229], off
	v_lshl_add_u64 v[220:221], s[8:9], 0, v[186:187]
	s_mov_b32 m0, s51
	v_lshl_add_u64 v[230:231], s[36:37], 0, v[184:185]
	global_load_lds_dwordx4 v[220:221], off
	v_lshl_add_u64 v[220:221], s[8:9], 0, v[190:191]
	s_add_i32 m0, s51, 0x2000
	v_lshl_add_u64 v[232:233], s[36:37], 0, v[188:189]
	global_load_lds_dwordx4 v[220:221], off
	s_mov_b32 m0, s89
	s_nop 0
	global_load_lds_dwordx4 v[230:231], off
	s_mov_b32 m0, s90
	s_nop 0
	global_load_lds_dwordx4 v[232:233], off
	s_waitcnt vmcnt(8)
	s_waitcnt lgkmcnt(0)
	s_barrier
; #define PG8_STAGE(bufoff, gbase, voff) do { _Pragma("unroll") for (int _i = 0; _i < 2; ++_i) \
;         __builtin_amdgcn_global_load_lds((const unsigned*)((const char*)(gbase) + (voff)[_i]), (LAS unsigned*)(lds + (bufoff) + ldsw + _i * 8192), 16, 0, 0); } while (0)
; #define PG8_LDA(dst, b, h) do { _Pragma("unroll") for (int m = 0; m < 4; ++m) _Pragma("unroll") for (int k = 0; k < 2; ++k) dst[m][k] = *(const LAS bf16x8*)(lds + PG8_SA(b, h) + aoff + m * 2048 + k * 1024); } while (0)
; #define PG8_LDB(dst, b, h) do { _Pragma("unroll") for (int n = 0; n < 2; ++n) _Pragma("unroll") for (int k = 0; k < 2; ++k) dst[n][k] = *(const LAS bf16x8*)(lds + PG8_SB(b, h) + boff + n * 2048 + k * 1024); } while (0)
; #define PG8_MMA(ai, bj, At, Bt) do { __builtin_amdgcn_s_setprio(1); _Pragma("unroll") for (int m = 0; m < 4; ++m) _Pragma("unroll") for (int n = 0; n < 2; ++n) _Pragma("unroll") for (int k = 0; k < 2; ++k) \
;         acc[ai][bj][m][n] = __builtin_amdgcn_mfma_f32_16x16x32_bf16(Bt[n][k], At[m][k], acc[ai][bj][m][n], 0, 0, 0); __builtin_amdgcn_s_setprio(0); } while (0)
; #define PG8_WAIT_V(n) asm volatile("s_waitcnt vmcnt(" #n ")" ::: "memory")
; #define PG8_WAIT_L(n) asm volatile("s_waitcnt lgkmcnt(" #n ")" ::: "memory")
; #define PG8_BAR __builtin_amdgcn_s_barrier()
; #define PG8_SCHED __builtin_amdgcn_sched_barrier(0)
; template <class Sched, class Epi, bool ALIGN_EPI, bool SP2>
; __device__ __forceinline__ void gemm_phase(LAS unsigned char* lds, const int K, const int lda, const int ldb, const Sched& S, const Epi& E) {
;     ...
;             PG8_WAIT_V(8); PG8_WAIT_L(0); PG8_BAR; PG8_MMA(1, 0, At, B0); PG8_MMA(1, 1, At, B1); PG8_BAR; PG8_SCHED;
;             PG8_LDB(B0, 1, 0); PG8_LDB(B1, 1, 1); PG8_SCHED; PG8_LDA(At, 1, 0); PG8_STAGE(PG8_SA(0, 1), a2 + hstepA, voffA);
;             PG8_WAIT_V(8); PG8_WAIT_L(0); PG8_BAR; PG8_MMA(0, 0, At, B0); PG8_MMA(0, 1, At, B1); PG8_BAR; PG8_SCHED;
;             PG8_LDA(At, 1, 1); PG8_STAGE(PG8_SB(1, 0), b3, voffB); PG8_STAGE(PG8_SB(1, 1), b3 + hstepB, voffB); PG8_STAGE(PG8_SA(1, 0), a3, voffA);
;             PG8_WAIT_V(8); PG8_WAIT_L(0); PG8_BAR; PG8_MMA(1, 0, At, B0); PG8_MMA(1, 1, At, B1); PG8_BAR; PG8_SCHED;
	s_setprio 1
	s_waitcnt lgkmcnt(0)
	v_mfma_f32_16x16x32_bf16 v[108:111], v[32:35], v[132:135], v[108:111]
	v_mfma_f32_16x16x32_bf16 v[104:107], v[48:51], v[132:135], v[104:107]
	v_mfma_f32_16x16x32_bf16 v[84:87], v[32:35], v[148:151], v[84:87]
	v_mfma_f32_16x16x32_bf16 v[72:75], v[48:51], v[148:151], v[72:75]
	v_mfma_f32_16x16x32_bf16 v[28:31], v[32:35], v[196:199], v[28:31]
	v_mfma_f32_16x16x32_bf16 v[24:27], v[48:51], v[196:199], v[24:27]
	v_mfma_f32_16x16x32_bf16 v[12:15], v[32:35], v[204:207], v[12:15]
	v_mfma_f32_16x16x32_bf16 v[8:11], v[48:51], v[204:207], v[8:11]
	v_mfma_f32_16x16x32_bf16 v[108:111], v[36:39], v[144:147], v[108:111]
	v_mfma_f32_16x16x32_bf16 v[104:107], v[52:55], v[144:147], v[104:107]
	v_mfma_f32_16x16x32_bf16 v[84:87], v[36:39], v[160:163], v[84:87]
	v_mfma_f32_16x16x32_bf16 v[72:75], v[52:55], v[160:163], v[72:75]
	v_mfma_f32_16x16x32_bf16 v[28:31], v[36:39], v[200:203], v[28:31]
	v_mfma_f32_16x16x32_bf16 v[24:27], v[52:55], v[200:203], v[24:27]
	v_mfma_f32_16x16x32_bf16 v[12:15], v[36:39], v[216:219], v[12:15]
	v_mfma_f32_16x16x32_bf16 v[8:11], v[52:55], v[216:219], v[8:11]
	s_setprio 0
	s_setprio 1
	v_mfma_f32_16x16x32_bf16 v[44:47], v[56:59], v[148:151], v[44:47]
	v_mfma_f32_16x16x32_bf16 v[40:43], v[64:67], v[148:151], v[40:43]
	v_mfma_f32_16x16x32_bf16 v[20:23], v[56:59], v[196:199], v[20:23]
	v_mfma_f32_16x16x32_bf16 v[16:19], v[64:67], v[196:199], v[16:19]
	v_mfma_f32_16x16x32_bf16 v[4:7], v[56:59], v[204:207], v[4:7]
	v_mfma_f32_16x16x32_bf16 v[0:3], v[64:67], v[204:207], v[0:3]
	v_mfma_f32_16x16x32_bf16 v[32:35], v[56:59], v[132:135], v[100:103]
	v_mfma_f32_16x16x32_bf16 v[36:39], v[64:67], v[132:135], v[96:99]
	v_mfma_f32_16x16x32_bf16 v[44:47], v[60:63], v[160:163], v[44:47]
	v_mfma_f32_16x16x32_bf16 v[40:43], v[68:71], v[160:163], v[40:43]
	v_mfma_f32_16x16x32_bf16 v[20:23], v[60:63], v[200:203], v[20:23]
	v_mfma_f32_16x16x32_bf16 v[16:19], v[68:71], v[200:203], v[16:19]
	v_mfma_f32_16x16x32_bf16 v[4:7], v[60:63], v[216:219], v[4:7]
	v_mfma_f32_16x16x32_bf16 v[0:3], v[68:71], v[216:219], v[0:3]
	v_mfma_f32_16x16x32_bf16 v[32:35], v[60:63], v[144:147], v[32:35]
	v_mfma_f32_16x16x32_bf16 v[36:39], v[68:71], v[144:147], v[36:39]
	s_setprio 0
	s_barrier
	s_add_i32 s51, 0, 0x18000
	s_add_i32 s17, 0, 0x1c000
	v_add_u32_e32 v60, s51, v183
	v_add_u32_e32 v96, s17, v183
	ds_read_b128 v[48:51], v60
	ds_read_b128 v[52:55], v60 offset:1024
	ds_read_b128 v[56:59], v60 offset:2048
	ds_read_b128 v[60:63], v60 offset:3072
	ds_read_b128 v[64:67], v96
	ds_read_b128 v[68:71], v96 offset:1024
	ds_read_b128 v[196:199], v96 offset:2048
	ds_read_b128 v[200:203], v96 offset:3072
	s_add_u32 s8, s36, 0x80000
	s_addc_u32 s9, s37, 0
	s_mov_b32 m0, s91
	v_lshl_add_u64 v[148:149], s[8:9], 0, v[184:185]
	ds_read_b128 v[96:99], v213 offset:32768
	ds_read_b128 v[100:103], v213 offset:33792
	ds_read_b128 v[132:135], v213 offset:34816
	ds_read_b128 v[144:147], v213 offset:35840
	ds_read_b128 v[204:207], v213 offset:36864
	ds_read_b128 v[216:219], v213 offset:37888
	ds_read_b128 v[220:223], v213 offset:38912
	ds_read_b128 v[224:227], v213 offset:39936
	global_load_lds_dwordx4 v[148:149], off
	v_lshl_add_u64 v[148:149], s[8:9], 0, v[188:189]
	s_mov_b32 m0, s96
	s_nop 0
	global_load_lds_dwordx4 v[148:149], off
	s_waitcnt vmcnt(8)
	s_waitcnt lgkmcnt(0)
	s_barrier
	s_setprio 1
	s_waitcnt lgkmcnt(0)
	v_mfma_f32_16x16x32_bf16 v[148:151], v[48:51], v[96:99], v[172:175]
	v_mfma_f32_16x16x32_bf16 v[172:175], v[52:55], v[100:103], v[148:151]
	v_mfma_f32_16x16x32_bf16 v[148:151], v[56:59], v[96:99], v[168:171]
	v_mfma_f32_16x16x32_bf16 v[168:171], v[60:63], v[100:103], v[148:151]
	v_mfma_f32_16x16x32_bf16 v[148:151], v[48:51], v[132:135], v[156:159]
	v_mfma_f32_16x16x32_bf16 v[156:159], v[52:55], v[144:147], v[148:151]
	v_mfma_f32_16x16x32_bf16 v[148:151], v[56:59], v[132:135], v[152:155]
	v_mfma_f32_16x16x32_bf16 v[140:143], v[48:51], v[204:207], v[140:143]
	v_mfma_f32_16x16x32_bf16 v[136:139], v[56:59], v[204:207], v[136:139]
	v_mfma_f32_16x16x32_bf16 v[124:127], v[48:51], v[220:223], v[124:127]
	v_mfma_f32_16x16x32_bf16 v[120:123], v[56:59], v[220:223], v[120:123]
	v_mfma_f32_16x16x32_bf16 v[152:155], v[60:63], v[144:147], v[148:151]
	v_mfma_f32_16x16x32_bf16 v[140:143], v[52:55], v[216:219], v[140:143]
	v_mfma_f32_16x16x32_bf16 v[136:139], v[60:63], v[216:219], v[136:139]
	v_mfma_f32_16x16x32_bf16 v[124:127], v[52:55], v[224:227], v[124:127]
	v_mfma_f32_16x16x32_bf16 v[120:123], v[60:63], v[224:227], v[120:123]
	s_setprio 0
	s_setprio 1
	v_mfma_f32_16x16x32_bf16 v[76:79], v[196:199], v[96:99], v[76:79]
	v_mfma_f32_16x16x32_bf16 v[148:151], v[64:67], v[96:99], v[164:167]
	v_mfma_f32_16x16x32_bf16 v[160:163], v[200:203], v[100:103], v[76:79]
	v_mfma_f32_16x16x32_bf16 v[76:79], v[64:67], v[132:135], v[80:83]
	v_mfma_f32_16x16x32_bf16 v[164:167], v[68:71], v[100:103], v[148:151]
	v_mfma_f32_16x16x32_bf16 v[148:151], v[68:71], v[144:147], v[76:79]
	v_mfma_f32_16x16x32_bf16 v[76:79], v[196:199], v[132:135], v[88:91]
	v_mfma_f32_16x16x32_bf16 v[144:147], v[200:203], v[144:147], v[76:79]
	v_mfma_f32_16x16x32_bf16 v[76:79], v[64:67], v[204:207], v[92:95]
	v_mfma_f32_16x16x32_bf16 v[132:135], v[68:71], v[216:219], v[76:79]
	v_mfma_f32_16x16x32_bf16 v[76:79], v[196:199], v[204:207], v[128:131]
	v_mfma_f32_16x16x32_bf16 v[128:131], v[200:203], v[216:219], v[76:79]
	v_mfma_f32_16x16x32_bf16 v[76:79], v[64:67], v[220:223], v[116:119]
	v_mfma_f32_16x16x32_bf16 v[116:119], v[68:71], v[224:227], v[76:79]
	v_mfma_f32_16x16x32_bf16 v[76:79], v[196:199], v[220:223], v[112:115]
	v_mfma_f32_16x16x32_bf16 v[112:115], v[200:203], v[224:227], v[76:79]
	s_setprio 0
	s_barrier
; #define PG8_STAGE(bufoff, gbase, voff) do { _Pragma("unroll") for (int _i = 0; _i < 2; ++_i) \
;         __builtin_amdgcn_global_load_lds((const unsigned*)((const char*)(gbase) + (voff)[_i]), (LAS unsigned*)(lds + (bufoff) + ldsw + _i * 8192), 16, 0, 0); } while (0)
; #define PG8_LDA(dst, b, h) do { _Pragma("unroll") for (int m = 0; m < 4; ++m) _Pragma("unroll") for (int k = 0; k < 2; ++k) dst[m][k] = *(const LAS bf16x8*)(lds + PG8_SA(b, h) + aoff + m * 2048 + k * 1024); } while (0)
; #define PG8_MMA(ai, bj, At, Bt) do { __builtin_amdgcn_s_setprio(1); _Pragma("unroll") for (int m = 0; m < 4; ++m) _Pragma("unroll") for (int n = 0; n < 2; ++n) _Pragma("unroll") for (int k = 0; k < 2; ++k) \
;         acc[ai][bj][m][n] = __builtin_amdgcn_mfma_f32_16x16x32_bf16(Bt[n][k], At[m][k], acc[ai][bj][m][n], 0, 0, 0); __builtin_amdgcn_s_setprio(0); } while (0)
; #define PG8_WAIT_V(n) asm volatile("s_waitcnt vmcnt(" #n ")" ::: "memory")
; #define PG8_WAIT_L(n) asm volatile("s_waitcnt lgkmcnt(" #n ")" ::: "memory")
; #define PG8_BAR __builtin_amdgcn_s_barrier()
; #define PG8_SCHED __builtin_amdgcn_sched_barrier(0)
; template <class Sched, class Epi, bool ALIGN_EPI, bool SP2>
; __device__ __forceinline__ void gemm_phase(LAS unsigned char* lds, const int K, const int lda, const int ldb, const Sched& S, const Epi& E) {
;     ...
;         for (int t = 0; t < nt; t += 2) {
;             const bool last = (t == nt - 2);
;             const char* a1 = cA + (size_t)(t + 1) * kstep;
;             const char* a2 = last ? nA : cA + (size_t)(t + 2) * kstep; const char* b2 = last ? nB : cB + (size_t)(t + 2) * kstep;
;             const char* a3 = a2 + kstep; const char* b3 = b2 + kstep;
;     ...
;             PG8_LDA(At, 1, 1); PG8_STAGE(PG8_SB(1, 0), b3, voffB); PG8_STAGE(PG8_SB(1, 1), b3 + hstepB, voffB); PG8_STAGE(PG8_SA(1, 0), a3, voffA);
;             PG8_WAIT_V(8); PG8_WAIT_L(0); PG8_BAR; PG8_MMA(1, 0, At, B0); PG8_MMA(1, 1, At, B1); PG8_BAR; PG8_SCHED;
	s_add_i32 s8, s51, s88
	v_lshl_add_u64 v[96:97], v[208:209], 0, s[10:11]
	s_mov_b32 m0, s8
	s_nop 1
	ds_read_b128 v[76:79], v213 offset:49152
	ds_read_b128 v[80:83], v213 offset:50176
	ds_read_b128 v[88:91], v213 offset:51200
	ds_read_b128 v[92:95], v213 offset:52224
	ds_read_b128 v[204:207], v213 offset:53248
	ds_read_b128 v[216:219], v213 offset:54272
	ds_read_b128 v[220:223], v213 offset:55296
	ds_read_b128 v[224:227], v213 offset:56320
	global_load_lds_dwordx4 v[96:97], off
	s_add_i32 m0, s8, 0x2000
	s_add_u32 s8, s28, 0x80080
	v_lshl_add_u64 v[96:97], v[228:229], 0, s[10:11]
	s_addc_u32 s9, s29, 0
	s_add_i32 s17, s17, s88
	global_load_lds_dwordx4 v[96:97], off
	v_lshl_add_u64 v[96:97], s[8:9], 0, v[186:187]
	s_mov_b32 m0, s17
	s_nop 0
	global_load_lds_dwordx4 v[96:97], off
	v_lshl_add_u64 v[96:97], s[8:9], 0, v[190:191]
	s_add_i32 m0, s17, 0x2000
	s_nop 0
	global_load_lds_dwordx4 v[96:97], off
	v_lshl_add_u64 v[96:97], v[230:231], 0, s[10:11]
	s_mov_b32 m0, s97
	s_nop 0
	global_load_lds_dwordx4 v[96:97], off
	v_lshl_add_u64 v[96:97], v[232:233], 0, s[10:11]
	s_mov_b32 m0, s84
	s_nop 0
	global_load_lds_dwordx4 v[96:97], off
	s_waitcnt vmcnt(8)
	s_waitcnt lgkmcnt(0)
	s_barrier
	s_setprio 1
	s_waitcnt lgkmcnt(0)
	v_mfma_f32_16x16x32_bf16 v[96:99], v[48:51], v[76:79], v[108:111]
	v_mfma_f32_16x16x32_bf16 v[108:111], v[52:55], v[80:83], v[96:99]
	v_mfma_f32_16x16x32_bf16 v[96:99], v[56:59], v[76:79], v[104:107]
	v_mfma_f32_16x16x32_bf16 v[84:87], v[48:51], v[88:91], v[84:87]
	v_mfma_f32_16x16x32_bf16 v[72:75], v[56:59], v[88:91], v[72:75]
	v_mfma_f32_16x16x32_bf16 v[28:31], v[48:51], v[204:207], v[28:31]
	v_mfma_f32_16x16x32_bf16 v[24:27], v[56:59], v[204:207], v[24:27]
	v_mfma_f32_16x16x32_bf16 v[12:15], v[48:51], v[220:223], v[12:15]
	v_mfma_f32_16x16x32_bf16 v[8:11], v[56:59], v[220:223], v[8:11]
	v_mfma_f32_16x16x32_bf16 v[104:107], v[60:63], v[80:83], v[96:99]
	v_mfma_f32_16x16x32_bf16 v[84:87], v[52:55], v[92:95], v[84:87]
	v_mfma_f32_16x16x32_bf16 v[72:75], v[60:63], v[92:95], v[72:75]
	v_mfma_f32_16x16x32_bf16 v[28:31], v[52:55], v[216:219], v[28:31]
	v_mfma_f32_16x16x32_bf16 v[24:27], v[60:63], v[216:219], v[24:27]
	v_mfma_f32_16x16x32_bf16 v[12:15], v[52:55], v[224:227], v[12:15]
	v_mfma_f32_16x16x32_bf16 v[8:11], v[60:63], v[224:227], v[8:11]
	s_setprio 0
	s_setprio 1
	v_mfma_f32_16x16x32_bf16 v[32:35], v[64:67], v[76:79], v[32:35]
	v_mfma_f32_16x16x32_bf16 v[100:103], v[68:71], v[80:83], v[32:35]
	v_mfma_f32_16x16x32_bf16 v[32:35], v[196:199], v[76:79], v[36:39]
	v_mfma_f32_16x16x32_bf16 v[96:99], v[200:203], v[80:83], v[32:35]
	v_mfma_f32_16x16x32_bf16 v[32:35], v[64:67], v[88:91], v[44:47]
	v_mfma_f32_16x16x32_bf16 v[44:47], v[68:71], v[92:95], v[32:35]
	v_mfma_f32_16x16x32_bf16 v[32:35], v[196:199], v[88:91], v[40:43]
	v_mfma_f32_16x16x32_bf16 v[20:23], v[64:67], v[204:207], v[20:23]
	v_mfma_f32_16x16x32_bf16 v[16:19], v[196:199], v[204:207], v[16:19]
	v_mfma_f32_16x16x32_bf16 v[4:7], v[64:67], v[220:223], v[4:7]
	v_mfma_f32_16x16x32_bf16 v[0:3], v[196:199], v[220:223], v[0:3]
	v_mfma_f32_16x16x32_bf16 v[40:43], v[200:203], v[92:95], v[32:35]
	v_mfma_f32_16x16x32_bf16 v[20:23], v[68:71], v[216:219], v[20:23]
	v_mfma_f32_16x16x32_bf16 v[16:19], v[200:203], v[216:219], v[16:19]
	v_mfma_f32_16x16x32_bf16 v[4:7], v[68:71], v[224:227], v[4:7]
	v_mfma_f32_16x16x32_bf16 v[0:3], v[200:203], v[224:227], v[0:3]
	s_setprio 0
	s_add_i32 s7, s7, 2
	s_add_u32 s26, s26, 0x100
	s_addc_u32 s27, s27, 0
	s_add_u32 vcc_hi, vcc_hi, 0x100
	s_addc_u32 s6, s6, 0
	s_cmp_gt_u32 s7, 29
	s_barrier
	s_cbranch_scc0 .LBB0_353
	s_and_b64 vcc, exec, s[12:13]
	s_cbranch_vccz .LBB0_356
	s_barrier

; #define PG8_STAGE(bufoff, gbase, voff) do { _Pragma("unroll") for (int _i = 0; _i < 2; ++_i) \
;         __builtin_amdgcn_global_load_lds((const unsigned*)((const char*)(gbase) + (voff)[_i]), (LAS unsigned*)(lds + (bufoff) + ldsw + _i * 8192), 16, 0, 0); } while (0)
; #define PG8_LDA(dst, b, h) do { _Pragma("unroll") for (int m = 0; m < 4; ++m) _Pragma("unroll") for (int k = 0; k < 2; ++k) dst[m][k] = *(const LAS bf16x8*)(lds + PG8_SA(b, h) + aoff + m * 2048 + k * 1024); } while (0)
; #define PG8_LDB(dst, b, h) do { _Pragma("unroll") for (int n = 0; n < 2; ++n) _Pragma("unroll") for (int k = 0; k < 2; ++k) dst[n][k] = *(const LAS bf16x8*)(lds + PG8_SB(b, h) + boff + n * 2048 + k * 1024); } while (0)
; #define PG8_MMA(ai, bj, At, Bt) do { __builtin_amdgcn_s_setprio(1); _Pragma("unroll") for (int m = 0; m < 4; ++m) _Pragma("unroll") for (int n = 0; n < 2; ++n) _Pragma("unroll") for (int k = 0; k < 2; ++k) \
;         acc[ai][bj][m][n] = __builtin_amdgcn_mfma_f32_16x16x32_bf16(Bt[n][k], At[m][k], acc[ai][bj][m][n], 0, 0, 0); __builtin_amdgcn_s_setprio(0); } while (0)
; #define PG8_WAIT_V(n) asm volatile("s_waitcnt vmcnt(" #n ")" ::: "memory")
; #define PG8_WAIT_L(n) asm volatile("s_waitcnt lgkmcnt(" #n ")" ::: "memory")
; #define PG8_BAR __builtin_amdgcn_s_barrier()
; template <class Sched, class Epi, bool ALIGN_EPI, bool SP2>
; __device__ __forceinline__ void gemm_phase(LAS unsigned char* lds, const int K, const int lda, const int ldb, const Sched& S, const Epi& E) {
;     ...
;         for (int t = 0; t < nt; t += 2) {
;             const bool last = (t == nt - 2);
;             const char* a1 = cA + (size_t)(t + 1) * kstep;
;             const char* a2 = last ? nA : cA + (size_t)(t + 2) * kstep; const char* b2 = last ? nB : cB + (size_t)(t + 2) * kstep;
;             const char* a3 = a2 + kstep; const char* b3 = b2 + kstep;
;             if constexpr (SP2) {
;             PG8_LDB(B0, 0, 0); PG8_LDB(B1, 0, 1); PG8_SCHED; PG8_LDA(At, 0, 0); PG8_STAGE(PG8_SA(1, 1), a1 + hstepA, voffA);
;             PG8_WAIT_V(8); PG8_WAIT_L(0); PG8_BAR; PG8_MMA(0, 0, At, B0); PG8_MMA(0, 1, At, B1); PG8_BAR; PG8_SCHED;
;             PG8_LDA(At, 0, 1); PG8_STAGE(PG8_SB(0, 0), b2, voffB); PG8_STAGE(PG8_SB(0, 1), b2 + hstepB, voffB); PG8_STAGE(PG8_SA(0, 0), a2, voffA);
;             PG8_WAIT_V(8); PG8_WAIT_L(0); PG8_BAR; PG8_MMA(1, 0, At, B0); PG8_MMA(1, 1, At, B1); PG8_BAR; PG8_SCHED;
.LBB0_945:
	ds_read_b128 v[52:55], v209
	ds_read_b128 v[56:59], v209 offset:1024
	ds_read_b128 v[64:67], v209 offset:2048
	ds_read_b128 v[68:71], v209 offset:3072
	ds_read_b128 v[72:75], v210
	ds_read_b128 v[76:79], v210 offset:1024
	ds_read_b128 v[88:91], v210 offset:2048
	ds_read_b128 v[92:95], v210 offset:3072
	s_add_u32 s42, s36, 0xfff80080
	s_addc_u32 s43, s37, -1
	s_cmp_eq_u32 s61, 28
	s_cselect_b32 s45, s27, s43
	s_cselect_b32 s44, s26, s42
	s_cselect_b32 s43, s29, s25
	s_cselect_b32 s42, s28, s1
	v_lshl_add_u64 v[206:207], s[36:37], 0, v[186:187]
	s_add_i32 m0, s21, 0xc000
	ds_read_b128 v[160:163], v211
	ds_read_b128 v[164:167], v211 offset:1024
	ds_read_b128 v[168:171], v211 offset:2048
	ds_read_b128 v[172:175], v211 offset:3072
	ds_read_b128 v[190:193], v211 offset:4096
	ds_read_b128 v[194:197], v211 offset:5120
	ds_read_b128 v[198:201], v211 offset:6144
	ds_read_b128 v[202:205], v211 offset:7168
	global_load_lds_dwordx4 v[206:207], off
	v_lshl_add_u64 v[206:207], s[36:37], 0, v[188:189]
	s_add_i32 m0, s21, 0xe000
	s_nop 0
	global_load_lds_dwordx4 v[206:207], off
	s_waitcnt vmcnt(8)
	s_waitcnt lgkmcnt(0)
	s_barrier
	s_setprio 1
	s_waitcnt lgkmcnt(0)
	v_mfma_f32_16x16x32_bf16 v[156:159], v[52:55], v[160:163], v[156:159]
	v_mfma_f32_16x16x32_bf16 v[152:155], v[64:67], v[160:163], v[152:155]
	v_mfma_f32_16x16x32_bf16 v[140:143], v[52:55], v[168:171], v[140:143]
	v_mfma_f32_16x16x32_bf16 v[136:139], v[64:67], v[168:171], v[136:139]
	v_mfma_f32_16x16x32_bf16 v[124:127], v[52:55], v[190:193], v[124:127]
	v_mfma_f32_16x16x32_bf16 v[120:123], v[64:67], v[190:193], v[120:123]
	v_mfma_f32_16x16x32_bf16 v[108:111], v[52:55], v[198:201], v[108:111]
	v_mfma_f32_16x16x32_bf16 v[104:107], v[64:67], v[198:201], v[104:107]
	v_mfma_f32_16x16x32_bf16 v[156:159], v[56:59], v[164:167], v[156:159]
	v_mfma_f32_16x16x32_bf16 v[152:155], v[68:71], v[164:167], v[152:155]
	v_mfma_f32_16x16x32_bf16 v[140:143], v[56:59], v[172:175], v[140:143]
	v_mfma_f32_16x16x32_bf16 v[136:139], v[68:71], v[172:175], v[136:139]
	v_mfma_f32_16x16x32_bf16 v[124:127], v[56:59], v[194:197], v[124:127]
	v_mfma_f32_16x16x32_bf16 v[120:123], v[68:71], v[194:197], v[120:123]
	v_mfma_f32_16x16x32_bf16 v[108:111], v[56:59], v[202:205], v[108:111]
	v_mfma_f32_16x16x32_bf16 v[104:107], v[68:71], v[202:205], v[104:107]
	s_setprio 0
	s_setprio 1
	v_mfma_f32_16x16x32_bf16 v[148:151], v[72:75], v[160:163], v[148:151]
	v_mfma_f32_16x16x32_bf16 v[144:147], v[88:91], v[160:163], v[144:147]
	v_mfma_f32_16x16x32_bf16 v[132:135], v[72:75], v[168:171], v[132:135]
	v_mfma_f32_16x16x32_bf16 v[128:131], v[88:91], v[168:171], v[128:131]
	v_mfma_f32_16x16x32_bf16 v[116:119], v[72:75], v[190:193], v[116:119]
	v_mfma_f32_16x16x32_bf16 v[112:115], v[88:91], v[190:193], v[112:115]
	v_mfma_f32_16x16x32_bf16 v[100:103], v[72:75], v[198:201], v[100:103]
	v_mfma_f32_16x16x32_bf16 v[96:99], v[88:91], v[198:201], v[96:99]
	v_mfma_f32_16x16x32_bf16 v[148:151], v[76:79], v[164:167], v[148:151]
	v_mfma_f32_16x16x32_bf16 v[144:147], v[92:95], v[164:167], v[144:147]
	v_mfma_f32_16x16x32_bf16 v[132:135], v[76:79], v[172:175], v[132:135]
	v_mfma_f32_16x16x32_bf16 v[128:131], v[92:95], v[172:175], v[128:131]
	v_mfma_f32_16x16x32_bf16 v[116:119], v[76:79], v[194:197], v[116:119]
	v_mfma_f32_16x16x32_bf16 v[112:115], v[92:95], v[194:197], v[112:115]
	v_mfma_f32_16x16x32_bf16 v[100:103], v[76:79], v[202:205], v[100:103]
	v_mfma_f32_16x16x32_bf16 v[96:99], v[92:95], v[202:205], v[96:99]
	s_setprio 0
	s_barrier
	s_add_i32 s62, s50, s19
	v_lshl_add_u64 v[206:207], s[42:43], 0, v[182:183]
	s_mov_b32 m0, s62
	ds_read_b128 v[160:163], v211 offset:16384
	ds_read_b128 v[164:167], v211 offset:17408
	ds_read_b128 v[168:171], v211 offset:18432
	ds_read_b128 v[172:175], v211 offset:19456
	ds_read_b128 v[190:193], v211 offset:20480
	ds_read_b128 v[194:197], v211 offset:21504
	ds_read_b128 v[198:201], v211 offset:22528
	ds_read_b128 v[202:205], v211 offset:23552
	global_load_lds_dwordx4 v[206:207], off
	s_add_i32 m0, s62, 0x2000
	s_add_u32 s62, s42, 0x80000
	v_lshl_add_u64 v[214:215], s[42:43], 0, v[184:185]
	s_addc_u32 s63, s43, 0
	s_add_i32 s64, s51, s19
	global_load_lds_dwordx4 v[214:215], off
	v_lshl_add_u64 v[216:217], s[62:63], 0, v[182:183]
	s_mov_b32 m0, s64
	v_lshl_add_u64 v[218:219], s[44:45], 0, v[184:185]
	global_load_lds_dwordx4 v[216:217], off
	v_lshl_add_u64 v[216:217], s[62:63], 0, v[184:185]
	s_add_i32 m0, s64, 0x2000
	s_nop 0
	global_load_lds_dwordx4 v[216:217], off
	v_lshl_add_u64 v[216:217], s[44:45], 0, v[182:183]
	s_mov_b32 m0, s21
	s_nop 0
	global_load_lds_dwordx4 v[216:217], off
	s_mov_b32 m0, s33
	s_nop 0
	global_load_lds_dwordx4 v[218:219], off
	s_waitcnt vmcnt(8)
	s_waitcnt lgkmcnt(0)
	s_barrier
; #define PG8_STAGE(bufoff, gbase, voff) do { _Pragma("unroll") for (int _i = 0; _i < 2; ++_i) \
;         __builtin_amdgcn_global_load_lds((const unsigned*)((const char*)(gbase) + (voff)[_i]), (LAS unsigned*)(lds + (bufoff) + ldsw + _i * 8192), 16, 0, 0); } while (0)
; #define PG8_LDA(dst, b, h) do { _Pragma("unroll") for (int m = 0; m < 4; ++m) _Pragma("unroll") for (int k = 0; k < 2; ++k) dst[m][k] = *(const LAS bf16x8*)(lds + PG8_SA(b, h) + aoff + m * 2048 + k * 1024); } while (0)
; #define PG8_LDB(dst, b, h) do { _Pragma("unroll") for (int n = 0; n < 2; ++n) _Pragma("unroll") for (int k = 0; k < 2; ++k) dst[n][k] = *(const LAS bf16x8*)(lds + PG8_SB(b, h) + boff + n * 2048 + k * 1024); } while (0)
; #define PG8_MMA(ai, bj, At, Bt) do { __builtin_amdgcn_s_setprio(1); _Pragma("unroll") for (int m = 0; m < 4; ++m) _Pragma("unroll") for (int n = 0; n < 2; ++n) _Pragma("unroll") for (int k = 0; k < 2; ++k) \
;         acc[ai][bj][m][n] = __builtin_amdgcn_mfma_f32_16x16x32_bf16(Bt[n][k], At[m][k], acc[ai][bj][m][n], 0, 0, 0); __builtin_amdgcn_s_setprio(0); } while (0)
; #define PG8_WAIT_V(n) asm volatile("s_waitcnt vmcnt(" #n ")" ::: "memory")
; #define PG8_WAIT_L(n) asm volatile("s_waitcnt lgkmcnt(" #n ")" ::: "memory")
; #define PG8_BAR __builtin_amdgcn_s_barrier()
; #define PG8_SCHED __builtin_amdgcn_sched_barrier(0)
; template <class Sched, class Epi, bool ALIGN_EPI, bool SP2>
; __device__ __forceinline__ void gemm_phase(LAS unsigned char* lds, const int K, const int lda, const int ldb, const Sched& S, const Epi& E) {
;     ...
;             PG8_WAIT_V(8); PG8_WAIT_L(0); PG8_BAR; PG8_MMA(1, 0, At, B0); PG8_MMA(1, 1, At, B1); PG8_BAR; PG8_SCHED;
;             PG8_LDB(B0, 1, 0); PG8_LDB(B1, 1, 1); PG8_SCHED; PG8_LDA(At, 1, 0); PG8_STAGE(PG8_SA(0, 1), a2 + hstepA, voffA);
;             PG8_WAIT_V(8); PG8_WAIT_L(0); PG8_BAR; PG8_MMA(0, 0, At, B0); PG8_MMA(0, 1, At, B1); PG8_BAR; PG8_SCHED;
	s_setprio 1
	s_waitcnt lgkmcnt(0)
	v_mfma_f32_16x16x32_bf16 v[84:87], v[52:55], v[160:163], v[84:87]
	v_mfma_f32_16x16x32_bf16 v[80:83], v[64:67], v[160:163], v[80:83]
	v_mfma_f32_16x16x32_bf16 v[44:47], v[52:55], v[168:171], v[44:47]
	v_mfma_f32_16x16x32_bf16 v[40:43], v[64:67], v[168:171], v[40:43]
	v_mfma_f32_16x16x32_bf16 v[28:31], v[52:55], v[190:193], v[28:31]
	v_mfma_f32_16x16x32_bf16 v[24:27], v[64:67], v[190:193], v[24:27]
	v_mfma_f32_16x16x32_bf16 v[12:15], v[52:55], v[198:201], v[12:15]
	v_mfma_f32_16x16x32_bf16 v[8:11], v[64:67], v[198:201], v[8:11]
	v_mfma_f32_16x16x32_bf16 v[84:87], v[56:59], v[164:167], v[84:87]
	v_mfma_f32_16x16x32_bf16 v[80:83], v[68:71], v[164:167], v[80:83]
	v_mfma_f32_16x16x32_bf16 v[44:47], v[56:59], v[172:175], v[44:47]
	v_mfma_f32_16x16x32_bf16 v[40:43], v[68:71], v[172:175], v[40:43]
	v_mfma_f32_16x16x32_bf16 v[28:31], v[56:59], v[194:197], v[28:31]
	v_mfma_f32_16x16x32_bf16 v[24:27], v[68:71], v[194:197], v[24:27]
	v_mfma_f32_16x16x32_bf16 v[12:15], v[56:59], v[202:205], v[12:15]
	v_mfma_f32_16x16x32_bf16 v[8:11], v[68:71], v[202:205], v[8:11]
	s_setprio 0
	s_setprio 1
	v_mfma_f32_16x16x32_bf16 v[48:51], v[88:91], v[160:163], v[48:51]
	v_mfma_f32_16x16x32_bf16 v[36:39], v[72:75], v[168:171], v[36:39]
	v_mfma_f32_16x16x32_bf16 v[32:35], v[88:91], v[168:171], v[32:35]
	v_mfma_f32_16x16x32_bf16 v[20:23], v[72:75], v[190:193], v[20:23]
	v_mfma_f32_16x16x32_bf16 v[16:19], v[88:91], v[190:193], v[16:19]
	v_mfma_f32_16x16x32_bf16 v[4:7], v[72:75], v[198:201], v[4:7]
	v_mfma_f32_16x16x32_bf16 v[0:3], v[88:91], v[198:201], v[0:3]
	v_mfma_f32_16x16x32_bf16 v[52:55], v[72:75], v[160:163], v[60:63]
	v_mfma_f32_16x16x32_bf16 v[48:51], v[92:95], v[164:167], v[48:51]
	v_mfma_f32_16x16x32_bf16 v[36:39], v[76:79], v[172:175], v[36:39]
	v_mfma_f32_16x16x32_bf16 v[32:35], v[92:95], v[172:175], v[32:35]
	v_mfma_f32_16x16x32_bf16 v[20:23], v[76:79], v[194:197], v[20:23]
	v_mfma_f32_16x16x32_bf16 v[16:19], v[92:95], v[194:197], v[16:19]
	v_mfma_f32_16x16x32_bf16 v[4:7], v[76:79], v[202:205], v[4:7]
	v_mfma_f32_16x16x32_bf16 v[0:3], v[92:95], v[202:205], v[0:3]
	v_mfma_f32_16x16x32_bf16 v[52:55], v[76:79], v[164:167], v[52:55]
	s_setprio 0
	s_barrier
	s_add_i32 s62, 0, 0x18000
	s_add_i32 s63, 0, 0x1c000
	v_add_u32_e32 v68, s62, v181
	v_add_u32_e32 v92, s63, v181
	ds_read_b128 v[56:59], v68
	ds_read_b128 v[60:63], v68 offset:1024
	ds_read_b128 v[64:67], v68 offset:2048
	ds_read_b128 v[68:71], v68 offset:3072
	ds_read_b128 v[72:75], v92
	ds_read_b128 v[76:79], v92 offset:1024
	ds_read_b128 v[88:91], v92 offset:2048
	ds_read_b128 v[92:95], v92 offset:3072
	s_add_u32 s44, s44, 0x80000
	s_addc_u32 s45, s45, 0
	s_mov_b32 m0, s35
	v_lshl_add_u64 v[220:221], s[44:45], 0, v[182:183]
	ds_read_b128 v[160:163], v211 offset:32768
	ds_read_b128 v[164:167], v211 offset:33792
	ds_read_b128 v[168:171], v211 offset:34816
	ds_read_b128 v[172:175], v211 offset:35840
	ds_read_b128 v[190:193], v211 offset:36864
	ds_read_b128 v[194:197], v211 offset:37888
	ds_read_b128 v[198:201], v211 offset:38912
	ds_read_b128 v[202:205], v211 offset:39936
	global_load_lds_dwordx4 v[220:221], off
	v_lshl_add_u64 v[220:221], s[44:45], 0, v[184:185]
	s_mov_b32 m0, s46
	s_nop 0
	global_load_lds_dwordx4 v[220:221], off
	s_waitcnt vmcnt(8)
	s_waitcnt lgkmcnt(0)
	s_barrier
	s_setprio 1
	s_waitcnt lgkmcnt(0)
	v_mfma_f32_16x16x32_bf16 v[156:159], v[56:59], v[160:163], v[156:159]
	v_mfma_f32_16x16x32_bf16 v[152:155], v[64:67], v[160:163], v[152:155]
	v_mfma_f32_16x16x32_bf16 v[140:143], v[56:59], v[168:171], v[140:143]
	v_mfma_f32_16x16x32_bf16 v[136:139], v[64:67], v[168:171], v[136:139]
	v_mfma_f32_16x16x32_bf16 v[124:127], v[56:59], v[190:193], v[124:127]
	v_mfma_f32_16x16x32_bf16 v[120:123], v[64:67], v[190:193], v[120:123]
	v_mfma_f32_16x16x32_bf16 v[108:111], v[56:59], v[198:201], v[108:111]
	v_mfma_f32_16x16x32_bf16 v[104:107], v[64:67], v[198:201], v[104:107]
	v_mfma_f32_16x16x32_bf16 v[156:159], v[60:63], v[164:167], v[156:159]
	v_mfma_f32_16x16x32_bf16 v[152:155], v[68:71], v[164:167], v[152:155]
	v_mfma_f32_16x16x32_bf16 v[140:143], v[60:63], v[172:175], v[140:143]
	v_mfma_f32_16x16x32_bf16 v[136:139], v[68:71], v[172:175], v[136:139]
	v_mfma_f32_16x16x32_bf16 v[124:127], v[60:63], v[194:197], v[124:127]
	v_mfma_f32_16x16x32_bf16 v[120:123], v[68:71], v[194:197], v[120:123]
	v_mfma_f32_16x16x32_bf16 v[108:111], v[60:63], v[202:205], v[108:111]
	v_mfma_f32_16x16x32_bf16 v[104:107], v[68:71], v[202:205], v[104:107]
	s_setprio 0
	s_setprio 1
	v_mfma_f32_16x16x32_bf16 v[148:151], v[72:75], v[160:163], v[148:151]
	v_mfma_f32_16x16x32_bf16 v[144:147], v[88:91], v[160:163], v[144:147]
	v_mfma_f32_16x16x32_bf16 v[132:135], v[72:75], v[168:171], v[132:135]
	v_mfma_f32_16x16x32_bf16 v[128:131], v[88:91], v[168:171], v[128:131]
	v_mfma_f32_16x16x32_bf16 v[116:119], v[72:75], v[190:193], v[116:119]
	v_mfma_f32_16x16x32_bf16 v[112:115], v[88:91], v[190:193], v[112:115]
	v_mfma_f32_16x16x32_bf16 v[100:103], v[72:75], v[198:201], v[100:103]
	v_mfma_f32_16x16x32_bf16 v[96:99], v[88:91], v[198:201], v[96:99]
	v_mfma_f32_16x16x32_bf16 v[148:151], v[76:79], v[164:167], v[148:151]
	v_mfma_f32_16x16x32_bf16 v[144:147], v[92:95], v[164:167], v[144:147]
	v_mfma_f32_16x16x32_bf16 v[132:135], v[76:79], v[172:175], v[132:135]
	v_mfma_f32_16x16x32_bf16 v[128:131], v[92:95], v[172:175], v[128:131]
	v_mfma_f32_16x16x32_bf16 v[116:119], v[76:79], v[194:197], v[116:119]
	v_mfma_f32_16x16x32_bf16 v[112:115], v[92:95], v[194:197], v[112:115]
	v_mfma_f32_16x16x32_bf16 v[100:103], v[76:79], v[202:205], v[100:103]
	v_mfma_f32_16x16x32_bf16 v[96:99], v[92:95], v[202:205], v[96:99]
	s_setprio 0
	s_barrier
; #define PG8_STAGE(bufoff, gbase, voff) do { _Pragma("unroll") for (int _i = 0; _i < 2; ++_i) \
;         __builtin_amdgcn_global_load_lds((const unsigned*)((const char*)(gbase) + (voff)[_i]), (LAS unsigned*)(lds + (bufoff) + ldsw + _i * 8192), 16, 0, 0); } while (0)
; #define PG8_LDA(dst, b, h) do { _Pragma("unroll") for (int m = 0; m < 4; ++m) _Pragma("unroll") for (int k = 0; k < 2; ++k) dst[m][k] = *(const LAS bf16x8*)(lds + PG8_SA(b, h) + aoff + m * 2048 + k * 1024); } while (0)
; #define PG8_MMA(ai, bj, At, Bt) do { __builtin_amdgcn_s_setprio(1); _Pragma("unroll") for (int m = 0; m < 4; ++m) _Pragma("unroll") for (int n = 0; n < 2; ++n) _Pragma("unroll") for (int k = 0; k < 2; ++k) \
;         acc[ai][bj][m][n] = __builtin_amdgcn_mfma_f32_16x16x32_bf16(Bt[n][k], At[m][k], acc[ai][bj][m][n], 0, 0, 0); __builtin_amdgcn_s_setprio(0); } while (0)
; #define PG8_WAIT_V(n) asm volatile("s_waitcnt vmcnt(" #n ")" ::: "memory")
; #define PG8_WAIT_L(n) asm volatile("s_waitcnt lgkmcnt(" #n ")" ::: "memory")
; #define PG8_BAR __builtin_amdgcn_s_barrier()
; #define PG8_SCHED __builtin_amdgcn_sched_barrier(0)
; template <class Sched, class Epi, bool ALIGN_EPI, bool SP2>
; __device__ __forceinline__ void gemm_phase(LAS unsigned char* lds, const int K, const int lda, const int ldb, const Sched& S, const Epi& E) {
;     ...
;         for (int t = 0; t < nt; t += 2) {
;             const bool last = (t == nt - 2);
;             const char* a1 = cA + (size_t)(t + 1) * kstep;
;             const char* a2 = last ? nA : cA + (size_t)(t + 2) * kstep; const char* b2 = last ? nB : cB + (size_t)(t + 2) * kstep;
;     ...
;             PG8_LDA(At, 1, 1); PG8_STAGE(PG8_SB(1, 0), b3, voffB); PG8_STAGE(PG8_SB(1, 1), b3 + hstepB, voffB); PG8_STAGE(PG8_SA(1, 0), a3, voffA);
;             PG8_WAIT_V(8); PG8_WAIT_L(0); PG8_BAR; PG8_MMA(1, 0, At, B0); PG8_MMA(1, 1, At, B1); PG8_BAR; PG8_SCHED;
	s_add_i32 s44, s62, s19
	v_lshl_add_u64 v[206:207], v[206:207], 0, s[14:15]
	s_mov_b32 m0, s44
	ds_read_b128 v[160:163], v211 offset:49152
	ds_read_b128 v[164:167], v211 offset:50176
	ds_read_b128 v[168:171], v211 offset:51200
	ds_read_b128 v[172:175], v211 offset:52224
	ds_read_b128 v[190:193], v211 offset:53248
	ds_read_b128 v[194:197], v211 offset:54272
	ds_read_b128 v[198:201], v211 offset:55296
	ds_read_b128 v[202:205], v211 offset:56320
	global_load_lds_dwordx4 v[206:207], off
	s_add_i32 m0, s44, 0x2000
	s_add_u32 s42, s42, 0x80080
	v_lshl_add_u64 v[206:207], v[214:215], 0, s[14:15]
	s_addc_u32 s43, s43, 0
	s_add_i32 s44, s63, s19
	global_load_lds_dwordx4 v[206:207], off
	v_lshl_add_u64 v[206:207], s[42:43], 0, v[182:183]
	s_mov_b32 m0, s44
	s_nop 0
	global_load_lds_dwordx4 v[206:207], off
	v_lshl_add_u64 v[206:207], s[42:43], 0, v[184:185]
	s_add_i32 m0, s44, 0x2000
	s_nop 0
	global_load_lds_dwordx4 v[206:207], off
	v_lshl_add_u64 v[206:207], v[216:217], 0, s[14:15]
	s_mov_b32 m0, s48
	s_nop 0
	global_load_lds_dwordx4 v[206:207], off
	v_lshl_add_u64 v[206:207], v[218:219], 0, s[14:15]
	s_mov_b32 m0, s49
	s_nop 0
	global_load_lds_dwordx4 v[206:207], off
	s_waitcnt vmcnt(8)
	s_waitcnt lgkmcnt(0)
	s_barrier
	s_setprio 1
	s_waitcnt lgkmcnt(0)
	v_mfma_f32_16x16x32_bf16 v[84:87], v[56:59], v[160:163], v[84:87]
	v_mfma_f32_16x16x32_bf16 v[80:83], v[64:67], v[160:163], v[80:83]
	v_mfma_f32_16x16x32_bf16 v[44:47], v[56:59], v[168:171], v[44:47]
	v_mfma_f32_16x16x32_bf16 v[40:43], v[64:67], v[168:171], v[40:43]
	v_mfma_f32_16x16x32_bf16 v[28:31], v[56:59], v[190:193], v[28:31]
	v_mfma_f32_16x16x32_bf16 v[24:27], v[64:67], v[190:193], v[24:27]
	v_mfma_f32_16x16x32_bf16 v[12:15], v[56:59], v[198:201], v[12:15]
	v_mfma_f32_16x16x32_bf16 v[8:11], v[64:67], v[198:201], v[8:11]
	v_mfma_f32_16x16x32_bf16 v[84:87], v[60:63], v[164:167], v[84:87]
	v_mfma_f32_16x16x32_bf16 v[80:83], v[68:71], v[164:167], v[80:83]
	v_mfma_f32_16x16x32_bf16 v[44:47], v[60:63], v[172:175], v[44:47]
	v_mfma_f32_16x16x32_bf16 v[40:43], v[68:71], v[172:175], v[40:43]
	v_mfma_f32_16x16x32_bf16 v[28:31], v[60:63], v[194:197], v[28:31]
	v_mfma_f32_16x16x32_bf16 v[24:27], v[68:71], v[194:197], v[24:27]
	v_mfma_f32_16x16x32_bf16 v[12:15], v[60:63], v[202:205], v[12:15]
	v_mfma_f32_16x16x32_bf16 v[8:11], v[68:71], v[202:205], v[8:11]
	s_setprio 0
	s_setprio 1
	v_mfma_f32_16x16x32_bf16 v[52:55], v[72:75], v[160:163], v[52:55]
	v_mfma_f32_16x16x32_bf16 v[48:51], v[88:91], v[160:163], v[48:51]
	v_mfma_f32_16x16x32_bf16 v[36:39], v[72:75], v[168:171], v[36:39]
	v_mfma_f32_16x16x32_bf16 v[32:35], v[88:91], v[168:171], v[32:35]
	v_mfma_f32_16x16x32_bf16 v[20:23], v[72:75], v[190:193], v[20:23]
	v_mfma_f32_16x16x32_bf16 v[16:19], v[88:91], v[190:193], v[16:19]
	v_mfma_f32_16x16x32_bf16 v[4:7], v[72:75], v[198:201], v[4:7]
	v_mfma_f32_16x16x32_bf16 v[0:3], v[88:91], v[198:201], v[0:3]
	v_mfma_f32_16x16x32_bf16 v[60:63], v[76:79], v[164:167], v[52:55]
	v_mfma_f32_16x16x32_bf16 v[48:51], v[92:95], v[164:167], v[48:51]
	v_mfma_f32_16x16x32_bf16 v[36:39], v[76:79], v[172:175], v[36:39]
	v_mfma_f32_16x16x32_bf16 v[32:35], v[92:95], v[172:175], v[32:35]
	v_mfma_f32_16x16x32_bf16 v[20:23], v[76:79], v[194:197], v[20:23]
	v_mfma_f32_16x16x32_bf16 v[16:19], v[92:95], v[194:197], v[16:19]
	v_mfma_f32_16x16x32_bf16 v[4:7], v[76:79], v[202:205], v[4:7]
	v_mfma_f32_16x16x32_bf16 v[0:3], v[92:95], v[202:205], v[0:3]
	s_setprio 0
	s_add_i32 s61, s61, 2
	s_add_u32 s36, s36, 0x100
	s_addc_u32 s37, s37, 0
	s_add_u32 s1, s1, 0x100
	s_addc_u32 s25, s25, 0
	s_cmp_gt_u32 s61, 29
	s_barrier
	s_cbranch_scc0 .LBB0_945
	s_and_b64 vcc, exec, s[16:17]
	s_cbranch_vccz .LBB0_948
	s_barrier

; #define PG8_STAGE(bufoff, gbase, voff) do { _Pragma("unroll") for (int _i = 0; _i < 2; ++_i) \
;         __builtin_amdgcn_global_load_lds((const unsigned*)((const char*)(gbase) + (voff)[_i]), (LAS unsigned*)(lds + (bufoff) + ldsw + _i * 8192), 16, 0, 0); } while (0)
; #define PG8_LDA(dst, b, h) do { _Pragma("unroll") for (int m = 0; m < 4; ++m) _Pragma("unroll") for (int k = 0; k < 2; ++k) dst[m][k] = *(const LAS bf16x8*)(lds + PG8_SA(b, h) + aoff + m * 2048 + k * 1024); } while (0)
; #define PG8_LDB(dst, b, h) do { _Pragma("unroll") for (int n = 0; n < 2; ++n) _Pragma("unroll") for (int k = 0; k < 2; ++k) dst[n][k] = *(const LAS bf16x8*)(lds + PG8_SB(b, h) + boff + n * 2048 + k * 1024); } while (0)
; #define PG8_MMA(ai, bj, At, Bt) do { __builtin_amdgcn_s_setprio(1); _Pragma("unroll") for (int m = 0; m < 4; ++m) _Pragma("unroll") for (int n = 0; n < 2; ++n) _Pragma("unroll") for (int k = 0; k < 2; ++k) \
;         acc[ai][bj][m][n] = __builtin_amdgcn_mfma_f32_16x16x32_bf16(Bt[n][k], At[m][k], acc[ai][bj][m][n], 0, 0, 0); __builtin_amdgcn_s_setprio(0); } while (0)
; #define PG8_WAIT_V(n) asm volatile("s_waitcnt vmcnt(" #n ")" ::: "memory")
; #define PG8_WAIT_L(n) asm volatile("s_waitcnt lgkmcnt(" #n ")" ::: "memory")
; #define PG8_BAR __builtin_amdgcn_s_barrier()
; #define PG8_SCHED __builtin_amdgcn_sched_barrier(0)
; template <class Sched, class Epi, bool ALIGN_EPI, bool SP2>
; __device__ __forceinline__ void gemm_phase(LAS unsigned char* lds, const int K, const int lda, const int ldb, const Sched& S, const Epi& E) {
;     ...
;             const bool last = (t == nt - 2);
;             const char* a1 = cA + (size_t)(t + 1) * kstep;
;             const char* a2 = last ? nA : cA + (size_t)(t + 2) * kstep; const char* b2 = last ? nB : cB + (size_t)(t + 2) * kstep;
;             const char* a3 = a2 + kstep; const char* b3 = b2 + kstep;
;             if constexpr (SP2) {
;             PG8_LDB(B0, 0, 0); PG8_LDB(B1, 0, 1); PG8_SCHED; PG8_LDA(At, 0, 0); PG8_STAGE(PG8_SA(1, 1), a1 + hstepA, voffA);
;             PG8_WAIT_V(8); PG8_WAIT_L(0); PG8_BAR; PG8_MMA(0, 0, At, B0); PG8_MMA(0, 1, At, B1); PG8_BAR; PG8_SCHED;
;             PG8_LDA(At, 0, 1); PG8_STAGE(PG8_SB(0, 0), b2, voffB); PG8_STAGE(PG8_SB(0, 1), b2 + hstepB, voffB); PG8_STAGE(PG8_SA(0, 0), a2, voffA);
.LBB0_1037:
	ds_read_b128 v[64:67], v183
	ds_read_b128 v[68:71], v183 offset:1024
	ds_read_b128 v[72:75], v183 offset:2048
	ds_read_b128 v[76:79], v183 offset:3072
	ds_read_b128 v[144:147], v184
	ds_read_b128 v[160:163], v184 offset:1024
	ds_read_b128 v[164:167], v184 offset:2048
	ds_read_b128 v[168:171], v184 offset:3072
	s_add_u32 s42, s36, 0xfff80080
	s_addc_u32 s43, s37, -1
	s_cmp_eq_u32 s57, 28
	s_cselect_b32 s45, s27, s43
	s_cselect_b32 s44, s26, s42
	s_cselect_b32 s43, s29, s56
	s_cselect_b32 s42, s28, s25
	v_lshl_add_u64 v[216:217], s[36:37], 0, v[156:157]
	s_add_i32 m0, s33, 0xc000
	ds_read_b128 v[172:175], v185
	ds_read_b128 v[188:191], v185 offset:1024
	ds_read_b128 v[192:195], v185 offset:2048
	ds_read_b128 v[196:199], v185 offset:3072
	ds_read_b128 v[200:203], v185 offset:4096
	ds_read_b128 v[204:207], v185 offset:5120
	ds_read_b128 v[208:211], v185 offset:6144
	ds_read_b128 v[212:215], v185 offset:7168
	global_load_lds_dwordx4 v[216:217], off
	v_lshl_add_u64 v[216:217], s[36:37], 0, v[158:159]
	s_add_i32 m0, s33, 0xe000
	s_nop 0
	global_load_lds_dwordx4 v[216:217], off
	s_waitcnt vmcnt(8)
	s_waitcnt lgkmcnt(0)
	s_barrier
	s_setprio 1
	s_waitcnt lgkmcnt(0)
	v_mfma_f32_16x16x32_bf16 v[140:143], v[64:67], v[172:175], v[140:143]
	v_mfma_f32_16x16x32_bf16 v[136:139], v[72:75], v[172:175], v[136:139]
	v_mfma_f32_16x16x32_bf16 v[124:127], v[64:67], v[192:195], v[124:127]
	v_mfma_f32_16x16x32_bf16 v[120:123], v[72:75], v[192:195], v[120:123]
	v_mfma_f32_16x16x32_bf16 v[108:111], v[64:67], v[200:203], v[108:111]
	v_mfma_f32_16x16x32_bf16 v[104:107], v[72:75], v[200:203], v[104:107]
	v_mfma_f32_16x16x32_bf16 v[92:95], v[64:67], v[208:211], v[92:95]
	v_mfma_f32_16x16x32_bf16 v[88:91], v[72:75], v[208:211], v[88:91]
	v_mfma_f32_16x16x32_bf16 v[140:143], v[68:71], v[188:191], v[140:143]
	v_mfma_f32_16x16x32_bf16 v[136:139], v[76:79], v[188:191], v[136:139]
	v_mfma_f32_16x16x32_bf16 v[124:127], v[68:71], v[196:199], v[124:127]
	v_mfma_f32_16x16x32_bf16 v[120:123], v[76:79], v[196:199], v[120:123]
	v_mfma_f32_16x16x32_bf16 v[108:111], v[68:71], v[204:207], v[108:111]
	v_mfma_f32_16x16x32_bf16 v[104:107], v[76:79], v[204:207], v[104:107]
	v_mfma_f32_16x16x32_bf16 v[92:95], v[68:71], v[212:215], v[92:95]
	v_mfma_f32_16x16x32_bf16 v[88:91], v[76:79], v[212:215], v[88:91]
	s_setprio 0
	s_setprio 1
	v_mfma_f32_16x16x32_bf16 v[132:135], v[144:147], v[172:175], v[132:135]
	v_mfma_f32_16x16x32_bf16 v[128:131], v[164:167], v[172:175], v[128:131]
	v_mfma_f32_16x16x32_bf16 v[116:119], v[144:147], v[192:195], v[116:119]
	v_mfma_f32_16x16x32_bf16 v[112:115], v[164:167], v[192:195], v[112:115]
	v_mfma_f32_16x16x32_bf16 v[100:103], v[144:147], v[200:203], v[100:103]
	v_mfma_f32_16x16x32_bf16 v[96:99], v[164:167], v[200:203], v[96:99]
	v_mfma_f32_16x16x32_bf16 v[84:87], v[144:147], v[208:211], v[84:87]
	v_mfma_f32_16x16x32_bf16 v[80:83], v[164:167], v[208:211], v[80:83]
	v_mfma_f32_16x16x32_bf16 v[132:135], v[160:163], v[188:191], v[132:135]
	v_mfma_f32_16x16x32_bf16 v[128:131], v[168:171], v[188:191], v[128:131]
	v_mfma_f32_16x16x32_bf16 v[116:119], v[160:163], v[196:199], v[116:119]
	v_mfma_f32_16x16x32_bf16 v[112:115], v[168:171], v[196:199], v[112:115]
	v_mfma_f32_16x16x32_bf16 v[100:103], v[160:163], v[204:207], v[100:103]
	v_mfma_f32_16x16x32_bf16 v[96:99], v[168:171], v[204:207], v[96:99]
	v_mfma_f32_16x16x32_bf16 v[84:87], v[160:163], v[212:215], v[84:87]
	v_mfma_f32_16x16x32_bf16 v[80:83], v[168:171], v[212:215], v[80:83]
	s_setprio 0
	s_barrier
	s_add_i32 s58, s51, s21
	v_lshl_add_u64 v[216:217], s[42:43], 0, v[150:151]
	s_mov_b32 m0, s58
	ds_read_b128 v[172:175], v185 offset:16384
	ds_read_b128 v[188:191], v185 offset:17408
	ds_read_b128 v[192:195], v185 offset:18432
	ds_read_b128 v[196:199], v185 offset:19456
	ds_read_b128 v[200:203], v185 offset:20480
	ds_read_b128 v[204:207], v185 offset:21504
	ds_read_b128 v[208:211], v185 offset:22528
	ds_read_b128 v[212:215], v185 offset:23552
	global_load_lds_dwordx4 v[216:217], off
	s_add_i32 m0, s58, 0x2000
	s_add_u32 s58, s42, 0x80000
	v_lshl_add_u64 v[218:219], s[42:43], 0, v[154:155]
	s_addc_u32 s59, s43, 0
	s_add_i32 s60, s52, s21
	global_load_lds_dwordx4 v[218:219], off
	v_lshl_add_u64 v[220:221], s[58:59], 0, v[150:151]
	s_mov_b32 m0, s60
	v_lshl_add_u64 v[222:223], s[44:45], 0, v[152:153]
	global_load_lds_dwordx4 v[220:221], off
	v_lshl_add_u64 v[220:221], s[58:59], 0, v[154:155]
	s_add_i32 m0, s60, 0x2000
	s_nop 0
	global_load_lds_dwordx4 v[220:221], off
	v_lshl_add_u64 v[220:221], s[44:45], 0, v[148:149]
	s_mov_b32 m0, s33
	s_nop 0
	global_load_lds_dwordx4 v[220:221], off
	s_mov_b32 m0, s35
	s_nop 0
	global_load_lds_dwordx4 v[222:223], off
	s_waitcnt vmcnt(8)
	s_waitcnt lgkmcnt(0)
	s_barrier
; #define PG8_STAGE(bufoff, gbase, voff) do { _Pragma("unroll") for (int _i = 0; _i < 2; ++_i) \
;         __builtin_amdgcn_global_load_lds((const unsigned*)((const char*)(gbase) + (voff)[_i]), (LAS unsigned*)(lds + (bufoff) + ldsw + _i * 8192), 16, 0, 0); } while (0)
; #define PG8_LDA(dst, b, h) do { _Pragma("unroll") for (int m = 0; m < 4; ++m) _Pragma("unroll") for (int k = 0; k < 2; ++k) dst[m][k] = *(const LAS bf16x8*)(lds + PG8_SA(b, h) + aoff + m * 2048 + k * 1024); } while (0)
; #define PG8_LDB(dst, b, h) do { _Pragma("unroll") for (int n = 0; n < 2; ++n) _Pragma("unroll") for (int k = 0; k < 2; ++k) dst[n][k] = *(const LAS bf16x8*)(lds + PG8_SB(b, h) + boff + n * 2048 + k * 1024); } while (0)
; #define PG8_MMA(ai, bj, At, Bt) do { __builtin_amdgcn_s_setprio(1); _Pragma("unroll") for (int m = 0; m < 4; ++m) _Pragma("unroll") for (int n = 0; n < 2; ++n) _Pragma("unroll") for (int k = 0; k < 2; ++k) \
;         acc[ai][bj][m][n] = __builtin_amdgcn_mfma_f32_16x16x32_bf16(Bt[n][k], At[m][k], acc[ai][bj][m][n], 0, 0, 0); __builtin_amdgcn_s_setprio(0); } while (0)
; #define PG8_WAIT_V(n) asm volatile("s_waitcnt vmcnt(" #n ")" ::: "memory")
; #define PG8_WAIT_L(n) asm volatile("s_waitcnt lgkmcnt(" #n ")" ::: "memory")
; #define PG8_BAR __builtin_amdgcn_s_barrier()
; #define PG8_SCHED __builtin_amdgcn_sched_barrier(0)
; template <class Sched, class Epi, bool ALIGN_EPI, bool SP2>
; __device__ __forceinline__ void gemm_phase(LAS unsigned char* lds, const int K, const int lda, const int ldb, const Sched& S, const Epi& E) {
;     ...
;             PG8_WAIT_V(8); PG8_WAIT_L(0); PG8_BAR; PG8_MMA(1, 0, At, B0); PG8_MMA(1, 1, At, B1); PG8_BAR; PG8_SCHED;
;             PG8_LDB(B0, 1, 0); PG8_LDB(B1, 1, 1); PG8_SCHED; PG8_LDA(At, 1, 0); PG8_STAGE(PG8_SA(0, 1), a2 + hstepA, voffA);
;             PG8_WAIT_V(8); PG8_WAIT_L(0); PG8_BAR; PG8_MMA(0, 0, At, B0); PG8_MMA(0, 1, At, B1); PG8_BAR; PG8_SCHED;
	s_setprio 1
	s_waitcnt lgkmcnt(0)
	v_mfma_f32_16x16x32_bf16 v[60:63], v[64:67], v[172:175], v[60:63]
	v_mfma_f32_16x16x32_bf16 v[56:59], v[72:75], v[172:175], v[56:59]
	v_mfma_f32_16x16x32_bf16 v[44:47], v[64:67], v[192:195], v[44:47]
	v_mfma_f32_16x16x32_bf16 v[40:43], v[72:75], v[192:195], v[40:43]
	v_mfma_f32_16x16x32_bf16 v[24:27], v[64:67], v[200:203], v[24:27]
	v_mfma_f32_16x16x32_bf16 v[20:23], v[72:75], v[200:203], v[20:23]
	v_mfma_f32_16x16x32_bf16 v[8:11], v[64:67], v[208:211], v[8:11]
	v_mfma_f32_16x16x32_bf16 v[0:3], v[72:75], v[208:211], v[0:3]
	v_mfma_f32_16x16x32_bf16 v[60:63], v[68:71], v[188:191], v[60:63]
	v_mfma_f32_16x16x32_bf16 v[56:59], v[76:79], v[188:191], v[56:59]
	v_mfma_f32_16x16x32_bf16 v[44:47], v[68:71], v[196:199], v[44:47]
	v_mfma_f32_16x16x32_bf16 v[40:43], v[76:79], v[196:199], v[40:43]
	v_mfma_f32_16x16x32_bf16 v[24:27], v[68:71], v[204:207], v[24:27]
	v_mfma_f32_16x16x32_bf16 v[20:23], v[76:79], v[204:207], v[20:23]
	v_mfma_f32_16x16x32_bf16 v[8:11], v[68:71], v[212:215], v[8:11]
	v_mfma_f32_16x16x32_bf16 v[0:3], v[76:79], v[212:215], v[0:3]
	s_setprio 0
	s_setprio 1
	v_mfma_f32_16x16x32_bf16 v[52:55], v[144:147], v[172:175], v[52:55]
	v_mfma_f32_16x16x32_bf16 v[48:51], v[164:167], v[172:175], v[48:51]
	v_mfma_f32_16x16x32_bf16 v[36:39], v[144:147], v[192:195], v[36:39]
	v_mfma_f32_16x16x32_bf16 v[32:35], v[164:167], v[192:195], v[32:35]
	v_mfma_f32_16x16x32_bf16 v[28:31], v[144:147], v[200:203], v[28:31]
	v_mfma_f32_16x16x32_bf16 v[16:19], v[164:167], v[200:203], v[16:19]
	v_mfma_f32_16x16x32_bf16 v[12:15], v[144:147], v[208:211], v[12:15]
	v_mfma_f32_16x16x32_bf16 v[4:7], v[164:167], v[208:211], v[4:7]
	v_mfma_f32_16x16x32_bf16 v[52:55], v[160:163], v[188:191], v[52:55]
	v_mfma_f32_16x16x32_bf16 v[48:51], v[168:171], v[188:191], v[48:51]
	v_mfma_f32_16x16x32_bf16 v[36:39], v[160:163], v[196:199], v[36:39]
	v_mfma_f32_16x16x32_bf16 v[32:35], v[168:171], v[196:199], v[32:35]
	v_mfma_f32_16x16x32_bf16 v[28:31], v[160:163], v[204:207], v[28:31]
	v_mfma_f32_16x16x32_bf16 v[16:19], v[168:171], v[204:207], v[16:19]
	v_mfma_f32_16x16x32_bf16 v[12:15], v[160:163], v[212:215], v[12:15]
	v_mfma_f32_16x16x32_bf16 v[4:7], v[168:171], v[212:215], v[4:7]
	s_setprio 0
	s_barrier
	s_add_i32 s58, 0, 0x18000
	s_add_i32 s59, 0, 0x1c000
	v_add_u32_e32 v76, s58, v181
	v_add_u32_e32 v168, s59, v181
	ds_read_b128 v[64:67], v76
	ds_read_b128 v[68:71], v76 offset:1024
	ds_read_b128 v[72:75], v76 offset:2048
	ds_read_b128 v[76:79], v76 offset:3072
	ds_read_b128 v[144:147], v168
	ds_read_b128 v[160:163], v168 offset:1024
	ds_read_b128 v[164:167], v168 offset:2048
	ds_read_b128 v[168:171], v168 offset:3072
	s_add_u32 s44, s44, 0x80000
	s_addc_u32 s45, s45, 0
	s_mov_b32 m0, s46
	v_lshl_add_u64 v[224:225], s[44:45], 0, v[148:149]
	ds_read_b128 v[172:175], v185 offset:32768
	ds_read_b128 v[188:191], v185 offset:33792
	ds_read_b128 v[192:195], v185 offset:34816
	ds_read_b128 v[196:199], v185 offset:35840
	ds_read_b128 v[200:203], v185 offset:36864
	ds_read_b128 v[204:207], v185 offset:37888
	ds_read_b128 v[208:211], v185 offset:38912
	ds_read_b128 v[212:215], v185 offset:39936
	global_load_lds_dwordx4 v[224:225], off
	v_lshl_add_u64 v[224:225], s[44:45], 0, v[152:153]
	s_mov_b32 m0, s47
	s_nop 0
	global_load_lds_dwordx4 v[224:225], off
	s_waitcnt vmcnt(8)
	s_waitcnt lgkmcnt(0)
	s_barrier
	s_setprio 1
	s_waitcnt lgkmcnt(0)
	v_mfma_f32_16x16x32_bf16 v[140:143], v[64:67], v[172:175], v[140:143]
	v_mfma_f32_16x16x32_bf16 v[136:139], v[72:75], v[172:175], v[136:139]
	v_mfma_f32_16x16x32_bf16 v[124:127], v[64:67], v[192:195], v[124:127]
	v_mfma_f32_16x16x32_bf16 v[120:123], v[72:75], v[192:195], v[120:123]
	v_mfma_f32_16x16x32_bf16 v[108:111], v[64:67], v[200:203], v[108:111]
	v_mfma_f32_16x16x32_bf16 v[104:107], v[72:75], v[200:203], v[104:107]
	v_mfma_f32_16x16x32_bf16 v[92:95], v[64:67], v[208:211], v[92:95]
	v_mfma_f32_16x16x32_bf16 v[88:91], v[72:75], v[208:211], v[88:91]
	v_mfma_f32_16x16x32_bf16 v[140:143], v[68:71], v[188:191], v[140:143]
	v_mfma_f32_16x16x32_bf16 v[136:139], v[76:79], v[188:191], v[136:139]
	v_mfma_f32_16x16x32_bf16 v[124:127], v[68:71], v[196:199], v[124:127]
	v_mfma_f32_16x16x32_bf16 v[120:123], v[76:79], v[196:199], v[120:123]
	v_mfma_f32_16x16x32_bf16 v[108:111], v[68:71], v[204:207], v[108:111]
	v_mfma_f32_16x16x32_bf16 v[104:107], v[76:79], v[204:207], v[104:107]
	v_mfma_f32_16x16x32_bf16 v[92:95], v[68:71], v[212:215], v[92:95]
	v_mfma_f32_16x16x32_bf16 v[88:91], v[76:79], v[212:215], v[88:91]
	s_setprio 0
	s_setprio 1
	v_mfma_f32_16x16x32_bf16 v[132:135], v[144:147], v[172:175], v[132:135]
	v_mfma_f32_16x16x32_bf16 v[128:131], v[164:167], v[172:175], v[128:131]
	v_mfma_f32_16x16x32_bf16 v[116:119], v[144:147], v[192:195], v[116:119]
	v_mfma_f32_16x16x32_bf16 v[112:115], v[164:167], v[192:195], v[112:115]
	v_mfma_f32_16x16x32_bf16 v[100:103], v[144:147], v[200:203], v[100:103]
	v_mfma_f32_16x16x32_bf16 v[96:99], v[164:167], v[200:203], v[96:99]
	v_mfma_f32_16x16x32_bf16 v[84:87], v[144:147], v[208:211], v[84:87]
	v_mfma_f32_16x16x32_bf16 v[80:83], v[164:167], v[208:211], v[80:83]
	v_mfma_f32_16x16x32_bf16 v[132:135], v[160:163], v[188:191], v[132:135]
	v_mfma_f32_16x16x32_bf16 v[128:131], v[168:171], v[188:191], v[128:131]
	v_mfma_f32_16x16x32_bf16 v[116:119], v[160:163], v[196:199], v[116:119]
	v_mfma_f32_16x16x32_bf16 v[112:115], v[168:171], v[196:199], v[112:115]
	v_mfma_f32_16x16x32_bf16 v[100:103], v[160:163], v[204:207], v[100:103]
	v_mfma_f32_16x16x32_bf16 v[96:99], v[168:171], v[204:207], v[96:99]
	v_mfma_f32_16x16x32_bf16 v[84:87], v[160:163], v[212:215], v[84:87]
	v_mfma_f32_16x16x32_bf16 v[80:83], v[168:171], v[212:215], v[80:83]
	s_setprio 0
	s_barrier
; #define PG8_STAGE(bufoff, gbase, voff) do { _Pragma("unroll") for (int _i = 0; _i < 2; ++_i) \
;         __builtin_amdgcn_global_load_lds((const unsigned*)((const char*)(gbase) + (voff)[_i]), (LAS unsigned*)(lds + (bufoff) + ldsw + _i * 8192), 16, 0, 0); } while (0)
; #define PG8_LDA(dst, b, h) do { _Pragma("unroll") for (int m = 0; m < 4; ++m) _Pragma("unroll") for (int k = 0; k < 2; ++k) dst[m][k] = *(const LAS bf16x8*)(lds + PG8_SA(b, h) + aoff + m * 2048 + k * 1024); } while (0)
; #define PG8_MMA(ai, bj, At, Bt) do { __builtin_amdgcn_s_setprio(1); _Pragma("unroll") for (int m = 0; m < 4; ++m) _Pragma("unroll") for (int n = 0; n < 2; ++n) _Pragma("unroll") for (int k = 0; k < 2; ++k) \
;         acc[ai][bj][m][n] = __builtin_amdgcn_mfma_f32_16x16x32_bf16(Bt[n][k], At[m][k], acc[ai][bj][m][n], 0, 0, 0); __builtin_amdgcn_s_setprio(0); } while (0)
; #define PG8_WAIT_V(n) asm volatile("s_waitcnt vmcnt(" #n ")" ::: "memory")
; #define PG8_WAIT_L(n) asm volatile("s_waitcnt lgkmcnt(" #n ")" ::: "memory")
; #define PG8_BAR __builtin_amdgcn_s_barrier()
; #define PG8_SCHED __builtin_amdgcn_sched_barrier(0)
; template <class Sched, class Epi, bool ALIGN_EPI, bool SP2>
; __device__ __forceinline__ void gemm_phase(LAS unsigned char* lds, const int K, const int lda, const int ldb, const Sched& S, const Epi& E) {
;     ...
;         for (int t = 0; t < nt; t += 2) {
;             const bool last = (t == nt - 2);
;             const char* a1 = cA + (size_t)(t + 1) * kstep;
;             const char* a2 = last ? nA : cA + (size_t)(t + 2) * kstep; const char* b2 = last ? nB : cB + (size_t)(t + 2) * kstep;
;     ...
;             PG8_LDA(At, 1, 1); PG8_STAGE(PG8_SB(1, 0), b3, voffB); PG8_STAGE(PG8_SB(1, 1), b3 + hstepB, voffB); PG8_STAGE(PG8_SA(1, 0), a3, voffA);
;             PG8_WAIT_V(8); PG8_WAIT_L(0); PG8_BAR; PG8_MMA(1, 0, At, B0); PG8_MMA(1, 1, At, B1); PG8_BAR; PG8_SCHED;
	s_add_i32 s44, s58, s21
	v_lshl_add_u64 v[216:217], v[216:217], 0, s[14:15]
	s_mov_b32 m0, s44
	ds_read_b128 v[172:175], v185 offset:49152
	ds_read_b128 v[188:191], v185 offset:50176
	ds_read_b128 v[192:195], v185 offset:51200
	ds_read_b128 v[196:199], v185 offset:52224
	ds_read_b128 v[200:203], v185 offset:53248
	ds_read_b128 v[204:207], v185 offset:54272
	ds_read_b128 v[208:211], v185 offset:55296
	ds_read_b128 v[212:215], v185 offset:56320
	global_load_lds_dwordx4 v[216:217], off
	s_add_i32 m0, s44, 0x2000
	s_add_u32 s42, s42, 0x80080
	v_lshl_add_u64 v[216:217], v[218:219], 0, s[14:15]
	s_addc_u32 s43, s43, 0
	s_add_i32 s44, s59, s21
	global_load_lds_dwordx4 v[216:217], off
	v_lshl_add_u64 v[216:217], s[42:43], 0, v[150:151]
	s_mov_b32 m0, s44
	s_nop 0
	global_load_lds_dwordx4 v[216:217], off
	v_lshl_add_u64 v[216:217], s[42:43], 0, v[154:155]
	s_add_i32 m0, s44, 0x2000
	s_nop 0
	global_load_lds_dwordx4 v[216:217], off
	v_lshl_add_u64 v[216:217], v[220:221], 0, s[14:15]
	s_mov_b32 m0, s49
	s_nop 0
	global_load_lds_dwordx4 v[216:217], off
	v_lshl_add_u64 v[216:217], v[222:223], 0, s[14:15]
	s_mov_b32 m0, s50
	s_nop 0
	global_load_lds_dwordx4 v[216:217], off
	s_waitcnt vmcnt(8)
	s_waitcnt lgkmcnt(0)
	s_barrier
	s_setprio 1
	s_waitcnt lgkmcnt(0)
	v_mfma_f32_16x16x32_bf16 v[60:63], v[64:67], v[172:175], v[60:63]
	v_mfma_f32_16x16x32_bf16 v[56:59], v[72:75], v[172:175], v[56:59]
	v_mfma_f32_16x16x32_bf16 v[44:47], v[64:67], v[192:195], v[44:47]
	v_mfma_f32_16x16x32_bf16 v[40:43], v[72:75], v[192:195], v[40:43]
	v_mfma_f32_16x16x32_bf16 v[24:27], v[64:67], v[200:203], v[24:27]
	v_mfma_f32_16x16x32_bf16 v[20:23], v[72:75], v[200:203], v[20:23]
	v_mfma_f32_16x16x32_bf16 v[8:11], v[64:67], v[208:211], v[8:11]
	v_mfma_f32_16x16x32_bf16 v[0:3], v[72:75], v[208:211], v[0:3]
	v_mfma_f32_16x16x32_bf16 v[60:63], v[68:71], v[188:191], v[60:63]
	v_mfma_f32_16x16x32_bf16 v[56:59], v[76:79], v[188:191], v[56:59]
	v_mfma_f32_16x16x32_bf16 v[44:47], v[68:71], v[196:199], v[44:47]
	v_mfma_f32_16x16x32_bf16 v[40:43], v[76:79], v[196:199], v[40:43]
	v_mfma_f32_16x16x32_bf16 v[24:27], v[68:71], v[204:207], v[24:27]
	v_mfma_f32_16x16x32_bf16 v[20:23], v[76:79], v[204:207], v[20:23]
	v_mfma_f32_16x16x32_bf16 v[8:11], v[68:71], v[212:215], v[8:11]
	v_mfma_f32_16x16x32_bf16 v[0:3], v[76:79], v[212:215], v[0:3]
	s_setprio 0
	s_setprio 1
	v_mfma_f32_16x16x32_bf16 v[52:55], v[144:147], v[172:175], v[52:55]
	v_mfma_f32_16x16x32_bf16 v[48:51], v[164:167], v[172:175], v[48:51]
	v_mfma_f32_16x16x32_bf16 v[36:39], v[144:147], v[192:195], v[36:39]
	v_mfma_f32_16x16x32_bf16 v[32:35], v[164:167], v[192:195], v[32:35]
	v_mfma_f32_16x16x32_bf16 v[28:31], v[144:147], v[200:203], v[28:31]
	v_mfma_f32_16x16x32_bf16 v[16:19], v[164:167], v[200:203], v[16:19]
	v_mfma_f32_16x16x32_bf16 v[12:15], v[144:147], v[208:211], v[12:15]
	v_mfma_f32_16x16x32_bf16 v[4:7], v[164:167], v[208:211], v[4:7]
	v_mfma_f32_16x16x32_bf16 v[52:55], v[160:163], v[188:191], v[52:55]
	v_mfma_f32_16x16x32_bf16 v[48:51], v[168:171], v[188:191], v[48:51]
	v_mfma_f32_16x16x32_bf16 v[36:39], v[160:163], v[196:199], v[36:39]
	v_mfma_f32_16x16x32_bf16 v[32:35], v[168:171], v[196:199], v[32:35]
	v_mfma_f32_16x16x32_bf16 v[28:31], v[160:163], v[204:207], v[28:31]
	v_mfma_f32_16x16x32_bf16 v[16:19], v[168:171], v[204:207], v[16:19]
	v_mfma_f32_16x16x32_bf16 v[12:15], v[160:163], v[212:215], v[12:15]
	v_mfma_f32_16x16x32_bf16 v[4:7], v[168:171], v[212:215], v[4:7]
	s_setprio 0
	s_add_i32 s57, s57, 2
	s_add_u32 s36, s36, 0x100
	s_addc_u32 s37, s37, 0
	s_add_u32 s25, s25, 0x100
	s_addc_u32 s56, s56, 0
	s_cmp_gt_u32 s57, 29
	s_barrier
	s_cbranch_scc0 .LBB0_1037
	s_and_b64 vcc, exec, s[16:17]
	s_mov_b32 s56, s62
	s_cbranch_vccz .LBB0_1040
	s_barrier

; #define PG8_STAGE(bufoff, gbase, voff) do { _Pragma("unroll") for (int _i = 0; _i < 2; ++_i) \
;         __builtin_amdgcn_global_load_lds((const unsigned*)((const char*)(gbase) + (voff)[_i]), (LAS unsigned*)(lds + (bufoff) + ldsw + _i * 8192), 16, 0, 0); } while (0)
; #define PG8_LDA(dst, b, h) do { _Pragma("unroll") for (int m = 0; m < 4; ++m) _Pragma("unroll") for (int k = 0; k < 2; ++k) dst[m][k] = *(const LAS bf16x8*)(lds + PG8_SA(b, h) + aoff + m * 2048 + k * 1024); } while (0)
; #define PG8_LDB(dst, b, h) do { _Pragma("unroll") for (int n = 0; n < 2; ++n) _Pragma("unroll") for (int k = 0; k < 2; ++k) dst[n][k] = *(const LAS bf16x8*)(lds + PG8_SB(b, h) + boff + n * 2048 + k * 1024); } while (0)
; #define PG8_MMA(ai, bj, At, Bt) do { __builtin_amdgcn_s_setprio(1); _Pragma("unroll") for (int m = 0; m < 4; ++m) _Pragma("unroll") for (int n = 0; n < 2; ++n) _Pragma("unroll") for (int k = 0; k < 2; ++k) \
;         acc[ai][bj][m][n] = __builtin_amdgcn_mfma_f32_16x16x32_bf16(Bt[n][k], At[m][k], acc[ai][bj][m][n], 0, 0, 0); __builtin_amdgcn_s_setprio(0); } while (0)
; #define PG8_WAIT_V(n) asm volatile("s_waitcnt vmcnt(" #n ")" ::: "memory")
; #define PG8_WAIT_L(n) asm volatile("s_waitcnt lgkmcnt(" #n ")" ::: "memory")
; #define PG8_BAR __builtin_amdgcn_s_barrier()
; #define PG8_SCHED __builtin_amdgcn_sched_barrier(0)
; template <class Sched, class Epi, bool ALIGN_EPI, bool SP2>
; __device__ __forceinline__ void gemm_phase(LAS unsigned char* lds, const int K, const int lda, const int ldb, const Sched& S, const Epi& E) {
;     ...
;             const bool last = (t == nt - 2);
;             const char* a1 = cA + (size_t)(t + 1) * kstep;
;             const char* a2 = last ? nA : cA + (size_t)(t + 2) * kstep; const char* b2 = last ? nB : cB + (size_t)(t + 2) * kstep;
;             const char* a3 = a2 + kstep; const char* b3 = b2 + kstep;
;             if constexpr (SP2) {
;             PG8_LDB(B0, 0, 0); PG8_LDB(B1, 0, 1); PG8_SCHED; PG8_LDA(At, 0, 0); PG8_STAGE(PG8_SA(1, 1), a1 + hstepA, voffA);
;             PG8_WAIT_V(8); PG8_WAIT_L(0); PG8_BAR; PG8_MMA(0, 0, At, B0); PG8_MMA(0, 1, At, B1); PG8_BAR; PG8_SCHED;
;             PG8_LDA(At, 0, 1); PG8_STAGE(PG8_SB(0, 0), b2, voffB); PG8_STAGE(PG8_SB(0, 1), b2 + hstepB, voffB); PG8_STAGE(PG8_SA(0, 0), a2, voffA);
.LBB0_1120:
	ds_read_b128 v[96:99], v178
	ds_read_b128 v[100:103], v178 offset:1024
	ds_read_b128 v[104:107], v178 offset:2048
	ds_read_b128 v[108:111], v178 offset:3072
	ds_read_b128 v[112:115], v180
	ds_read_b128 v[116:119], v180 offset:1024
	ds_read_b128 v[120:123], v180 offset:2048
	ds_read_b128 v[124:127], v180 offset:3072
	s_add_u32 s4, s0, 0x100
	s_addc_u32 s5, s1, 0
	s_cmpk_eq_i32 s51, 0x54
	s_cselect_b32 s27, s21, s5
	s_cselect_b32 s26, s20, s4
	s_cselect_b32 s25, s23, s50
	s_cselect_b32 s24, s22, s49
	v_lshl_add_u64 v[172:173], s[0:1], 0, v[164:165]
	s_add_i32 m0, s17, 0xc000
	ds_read_b128 v[168:171], v181
	ds_read_b128 v[184:187], v181 offset:1024
	ds_read_b128 v[188:191], v181 offset:2048
	ds_read_b128 v[192:195], v181 offset:3072
	ds_read_b128 v[196:199], v181 offset:4096
	ds_read_b128 v[200:203], v181 offset:5120
	ds_read_b128 v[204:207], v181 offset:6144
	ds_read_b128 v[208:211], v181 offset:7168
	global_load_lds_dwordx4 v[172:173], off
	v_lshl_add_u64 v[172:173], s[0:1], 0, v[166:167]
	s_add_i32 m0, s17, 0xe000
	s_nop 0
	global_load_lds_dwordx4 v[172:173], off
	s_waitcnt vmcnt(8)
	s_waitcnt lgkmcnt(0)
	s_barrier
	s_setprio 1
	s_waitcnt lgkmcnt(0)
	v_mfma_f32_16x16x32_bf16 v[156:159], v[96:99], v[168:171], v[156:159]
	v_mfma_f32_16x16x32_bf16 v[152:155], v[104:107], v[168:171], v[152:155]
	v_mfma_f32_16x16x32_bf16 v[144:147], v[96:99], v[188:191], v[144:147]
	v_mfma_f32_16x16x32_bf16 v[136:139], v[104:107], v[188:191], v[136:139]
	v_mfma_f32_16x16x32_bf16 v[92:95], v[96:99], v[196:199], v[92:95]
	v_mfma_f32_16x16x32_bf16 v[88:91], v[104:107], v[196:199], v[88:91]
	v_mfma_f32_16x16x32_bf16 v[80:83], v[96:99], v[204:207], v[80:83]
	v_mfma_f32_16x16x32_bf16 v[72:75], v[104:107], v[204:207], v[72:75]
	v_mfma_f32_16x16x32_bf16 v[156:159], v[100:103], v[184:187], v[156:159]
	v_mfma_f32_16x16x32_bf16 v[152:155], v[108:111], v[184:187], v[152:155]
	v_mfma_f32_16x16x32_bf16 v[144:147], v[100:103], v[192:195], v[144:147]
	v_mfma_f32_16x16x32_bf16 v[136:139], v[108:111], v[192:195], v[136:139]
	v_mfma_f32_16x16x32_bf16 v[92:95], v[100:103], v[200:203], v[92:95]
	v_mfma_f32_16x16x32_bf16 v[88:91], v[108:111], v[200:203], v[88:91]
	v_mfma_f32_16x16x32_bf16 v[80:83], v[100:103], v[208:211], v[80:83]
	v_mfma_f32_16x16x32_bf16 v[72:75], v[108:111], v[208:211], v[72:75]
	s_setprio 0
	s_setprio 1
	v_mfma_f32_16x16x32_bf16 v[148:151], v[112:115], v[168:171], v[148:151]
	v_mfma_f32_16x16x32_bf16 v[140:143], v[120:123], v[168:171], v[140:143]
	v_mfma_f32_16x16x32_bf16 v[132:135], v[112:115], v[188:191], v[132:135]
	v_mfma_f32_16x16x32_bf16 v[128:131], v[120:123], v[188:191], v[128:131]
	v_mfma_f32_16x16x32_bf16 v[84:87], v[112:115], v[196:199], v[84:87]
	v_mfma_f32_16x16x32_bf16 v[76:79], v[120:123], v[196:199], v[76:79]
	v_mfma_f32_16x16x32_bf16 v[68:71], v[112:115], v[204:207], v[68:71]
	v_mfma_f32_16x16x32_bf16 v[64:67], v[120:123], v[204:207], v[64:67]
	v_mfma_f32_16x16x32_bf16 v[148:151], v[116:119], v[184:187], v[148:151]
	v_mfma_f32_16x16x32_bf16 v[140:143], v[124:127], v[184:187], v[140:143]
	v_mfma_f32_16x16x32_bf16 v[132:135], v[116:119], v[192:195], v[132:135]
	v_mfma_f32_16x16x32_bf16 v[128:131], v[124:127], v[192:195], v[128:131]
	v_mfma_f32_16x16x32_bf16 v[84:87], v[116:119], v[200:203], v[84:87]
	v_mfma_f32_16x16x32_bf16 v[76:79], v[124:127], v[200:203], v[76:79]
	v_mfma_f32_16x16x32_bf16 v[68:71], v[116:119], v[208:211], v[68:71]
	v_mfma_f32_16x16x32_bf16 v[64:67], v[124:127], v[208:211], v[64:67]
	s_setprio 0
	s_barrier
	s_add_i32 s0, s42, s15
	v_lshl_add_u64 v[172:173], s[24:25], 0, v[160:161]
	s_mov_b32 m0, s0
	ds_read_b128 v[168:171], v181 offset:16384
	ds_read_b128 v[184:187], v181 offset:17408
	ds_read_b128 v[188:191], v181 offset:18432
	ds_read_b128 v[192:195], v181 offset:19456
	ds_read_b128 v[196:199], v181 offset:20480
	ds_read_b128 v[200:203], v181 offset:21504
	ds_read_b128 v[204:207], v181 offset:22528
	ds_read_b128 v[208:211], v181 offset:23552
	global_load_lds_dwordx4 v[172:173], off
	s_add_i32 m0, s0, 0x2000
	s_add_u32 s0, s24, 0x160000
	v_lshl_add_u64 v[212:213], s[24:25], 0, v[162:163]
	s_addc_u32 s1, s25, 0
	s_add_i32 s52, s43, s15
	global_load_lds_dwordx4 v[212:213], off
	v_lshl_add_u64 v[214:215], s[0:1], 0, v[160:161]
	s_mov_b32 m0, s52
	v_lshl_add_u64 v[216:217], s[26:27], 0, v[162:163]
	global_load_lds_dwordx4 v[214:215], off
	v_lshl_add_u64 v[214:215], s[0:1], 0, v[162:163]
	s_add_i32 m0, s52, 0x2000
	s_nop 0
	global_load_lds_dwordx4 v[214:215], off
	v_lshl_add_u64 v[214:215], s[26:27], 0, v[160:161]
	s_mov_b32 m0, s17
	s_nop 0
	global_load_lds_dwordx4 v[214:215], off
	s_mov_b32 m0, s28
	s_nop 0
	global_load_lds_dwordx4 v[216:217], off
	s_waitcnt vmcnt(8)
	s_waitcnt lgkmcnt(0)
	s_barrier
; #define PG8_STAGE(bufoff, gbase, voff) do { _Pragma("unroll") for (int _i = 0; _i < 2; ++_i) \
;         __builtin_amdgcn_global_load_lds((const unsigned*)((const char*)(gbase) + (voff)[_i]), (LAS unsigned*)(lds + (bufoff) + ldsw + _i * 8192), 16, 0, 0); } while (0)
; #define PG8_LDA(dst, b, h) do { _Pragma("unroll") for (int m = 0; m < 4; ++m) _Pragma("unroll") for (int k = 0; k < 2; ++k) dst[m][k] = *(const LAS bf16x8*)(lds + PG8_SA(b, h) + aoff + m * 2048 + k * 1024); } while (0)
; #define PG8_LDB(dst, b, h) do { _Pragma("unroll") for (int n = 0; n < 2; ++n) _Pragma("unroll") for (int k = 0; k < 2; ++k) dst[n][k] = *(const LAS bf16x8*)(lds + PG8_SB(b, h) + boff + n * 2048 + k * 1024); } while (0)
; #define PG8_MMA(ai, bj, At, Bt) do { __builtin_amdgcn_s_setprio(1); _Pragma("unroll") for (int m = 0; m < 4; ++m) _Pragma("unroll") for (int n = 0; n < 2; ++n) _Pragma("unroll") for (int k = 0; k < 2; ++k) \
;         acc[ai][bj][m][n] = __builtin_amdgcn_mfma_f32_16x16x32_bf16(Bt[n][k], At[m][k], acc[ai][bj][m][n], 0, 0, 0); __builtin_amdgcn_s_setprio(0); } while (0)
; #define PG8_WAIT_V(n) asm volatile("s_waitcnt vmcnt(" #n ")" ::: "memory")
; #define PG8_WAIT_L(n) asm volatile("s_waitcnt lgkmcnt(" #n ")" ::: "memory")
; #define PG8_BAR __builtin_amdgcn_s_barrier()
; #define PG8_SCHED __builtin_amdgcn_sched_barrier(0)
; template <class Sched, class Epi, bool ALIGN_EPI, bool SP2>
; __device__ __forceinline__ void gemm_phase(LAS unsigned char* lds, const int K, const int lda, const int ldb, const Sched& S, const Epi& E) {
;     ...
;             PG8_WAIT_V(8); PG8_WAIT_L(0); PG8_BAR; PG8_MMA(1, 0, At, B0); PG8_MMA(1, 1, At, B1); PG8_BAR; PG8_SCHED;
;             PG8_LDB(B0, 1, 0); PG8_LDB(B1, 1, 1); PG8_SCHED; PG8_LDA(At, 1, 0); PG8_STAGE(PG8_SA(0, 1), a2 + hstepA, voffA);
;             PG8_WAIT_V(8); PG8_WAIT_L(0); PG8_BAR; PG8_MMA(0, 0, At, B0); PG8_MMA(0, 1, At, B1); PG8_BAR; PG8_SCHED;
	s_setprio 1
	s_waitcnt lgkmcnt(0)
	v_mfma_f32_16x16x32_bf16 v[60:63], v[96:99], v[168:171], v[60:63]
	v_mfma_f32_16x16x32_bf16 v[56:59], v[104:107], v[168:171], v[56:59]
	v_mfma_f32_16x16x32_bf16 v[48:51], v[96:99], v[188:191], v[48:51]
	v_mfma_f32_16x16x32_bf16 v[40:43], v[104:107], v[188:191], v[40:43]
	v_mfma_f32_16x16x32_bf16 v[28:31], v[96:99], v[196:199], v[28:31]
	v_mfma_f32_16x16x32_bf16 v[24:27], v[104:107], v[196:199], v[24:27]
	v_mfma_f32_16x16x32_bf16 v[16:19], v[96:99], v[204:207], v[16:19]
	v_mfma_f32_16x16x32_bf16 v[8:11], v[104:107], v[204:207], v[8:11]
	v_mfma_f32_16x16x32_bf16 v[60:63], v[100:103], v[184:187], v[60:63]
	v_mfma_f32_16x16x32_bf16 v[56:59], v[108:111], v[184:187], v[56:59]
	v_mfma_f32_16x16x32_bf16 v[48:51], v[100:103], v[192:195], v[48:51]
	v_mfma_f32_16x16x32_bf16 v[40:43], v[108:111], v[192:195], v[40:43]
	v_mfma_f32_16x16x32_bf16 v[28:31], v[100:103], v[200:203], v[28:31]
	v_mfma_f32_16x16x32_bf16 v[24:27], v[108:111], v[200:203], v[24:27]
	v_mfma_f32_16x16x32_bf16 v[16:19], v[100:103], v[208:211], v[16:19]
	v_mfma_f32_16x16x32_bf16 v[8:11], v[108:111], v[208:211], v[8:11]
	s_setprio 0
	s_setprio 1
	v_mfma_f32_16x16x32_bf16 v[52:55], v[112:115], v[168:171], v[52:55]
	v_mfma_f32_16x16x32_bf16 v[44:47], v[120:123], v[168:171], v[44:47]
	v_mfma_f32_16x16x32_bf16 v[36:39], v[112:115], v[188:191], v[36:39]
	v_mfma_f32_16x16x32_bf16 v[32:35], v[120:123], v[188:191], v[32:35]
	v_mfma_f32_16x16x32_bf16 v[20:23], v[112:115], v[196:199], v[20:23]
	v_mfma_f32_16x16x32_bf16 v[12:15], v[120:123], v[196:199], v[12:15]
	v_mfma_f32_16x16x32_bf16 v[4:7], v[112:115], v[204:207], v[4:7]
	v_mfma_f32_16x16x32_bf16 v[0:3], v[120:123], v[204:207], v[0:3]
	v_mfma_f32_16x16x32_bf16 v[52:55], v[116:119], v[184:187], v[52:55]
	v_mfma_f32_16x16x32_bf16 v[44:47], v[124:127], v[184:187], v[44:47]
	v_mfma_f32_16x16x32_bf16 v[36:39], v[116:119], v[192:195], v[36:39]
	v_mfma_f32_16x16x32_bf16 v[32:35], v[124:127], v[192:195], v[32:35]
	v_mfma_f32_16x16x32_bf16 v[20:23], v[116:119], v[200:203], v[20:23]
	v_mfma_f32_16x16x32_bf16 v[12:15], v[124:127], v[200:203], v[12:15]
	v_mfma_f32_16x16x32_bf16 v[4:7], v[116:119], v[208:211], v[4:7]
	v_mfma_f32_16x16x32_bf16 v[0:3], v[124:127], v[208:211], v[0:3]
	s_setprio 0
	s_barrier
	s_add_i32 s52, 0, 0x18000
	s_add_i32 s53, 0, 0x1c000
	v_add_u32_e32 v108, s52, v175
	v_add_u32_e32 v124, s53, v175
	ds_read_b128 v[96:99], v108
	ds_read_b128 v[100:103], v108 offset:1024
	ds_read_b128 v[104:107], v108 offset:2048
	ds_read_b128 v[108:111], v108 offset:3072
	ds_read_b128 v[112:115], v124
	ds_read_b128 v[116:119], v124 offset:1024
	ds_read_b128 v[120:123], v124 offset:2048
	ds_read_b128 v[124:127], v124 offset:3072
	s_add_u32 s0, s26, 0x160000
	s_addc_u32 s1, s27, 0
	s_mov_b32 m0, s29
	v_lshl_add_u64 v[218:219], s[0:1], 0, v[160:161]
	ds_read_b128 v[168:171], v181 offset:32768
	ds_read_b128 v[184:187], v181 offset:33792
	ds_read_b128 v[188:191], v181 offset:34816
	ds_read_b128 v[192:195], v181 offset:35840
	ds_read_b128 v[196:199], v181 offset:36864
	ds_read_b128 v[200:203], v181 offset:37888
	ds_read_b128 v[204:207], v181 offset:38912
	ds_read_b128 v[208:211], v181 offset:39936
	global_load_lds_dwordx4 v[218:219], off
	v_lshl_add_u64 v[218:219], s[0:1], 0, v[162:163]
	s_mov_b32 m0, s33
	s_nop 0
	global_load_lds_dwordx4 v[218:219], off
	s_waitcnt vmcnt(8)
	s_waitcnt lgkmcnt(0)
	s_barrier
	s_setprio 1
	s_waitcnt lgkmcnt(0)
	v_mfma_f32_16x16x32_bf16 v[156:159], v[96:99], v[168:171], v[156:159]
	v_mfma_f32_16x16x32_bf16 v[152:155], v[104:107], v[168:171], v[152:155]
	v_mfma_f32_16x16x32_bf16 v[144:147], v[96:99], v[188:191], v[144:147]
	v_mfma_f32_16x16x32_bf16 v[136:139], v[104:107], v[188:191], v[136:139]
	v_mfma_f32_16x16x32_bf16 v[92:95], v[96:99], v[196:199], v[92:95]
	v_mfma_f32_16x16x32_bf16 v[88:91], v[104:107], v[196:199], v[88:91]
	v_mfma_f32_16x16x32_bf16 v[80:83], v[96:99], v[204:207], v[80:83]
	v_mfma_f32_16x16x32_bf16 v[72:75], v[104:107], v[204:207], v[72:75]
	v_mfma_f32_16x16x32_bf16 v[156:159], v[100:103], v[184:187], v[156:159]
	v_mfma_f32_16x16x32_bf16 v[152:155], v[108:111], v[184:187], v[152:155]
	v_mfma_f32_16x16x32_bf16 v[144:147], v[100:103], v[192:195], v[144:147]
	v_mfma_f32_16x16x32_bf16 v[136:139], v[108:111], v[192:195], v[136:139]
	v_mfma_f32_16x16x32_bf16 v[92:95], v[100:103], v[200:203], v[92:95]
	v_mfma_f32_16x16x32_bf16 v[88:91], v[108:111], v[200:203], v[88:91]
	v_mfma_f32_16x16x32_bf16 v[80:83], v[100:103], v[208:211], v[80:83]
	v_mfma_f32_16x16x32_bf16 v[72:75], v[108:111], v[208:211], v[72:75]
	s_setprio 0
	s_setprio 1
	v_mfma_f32_16x16x32_bf16 v[148:151], v[112:115], v[168:171], v[148:151]
	v_mfma_f32_16x16x32_bf16 v[140:143], v[120:123], v[168:171], v[140:143]
	v_mfma_f32_16x16x32_bf16 v[132:135], v[112:115], v[188:191], v[132:135]
	v_mfma_f32_16x16x32_bf16 v[128:131], v[120:123], v[188:191], v[128:131]
	v_mfma_f32_16x16x32_bf16 v[84:87], v[112:115], v[196:199], v[84:87]
	v_mfma_f32_16x16x32_bf16 v[76:79], v[120:123], v[196:199], v[76:79]
	v_mfma_f32_16x16x32_bf16 v[68:71], v[112:115], v[204:207], v[68:71]
	v_mfma_f32_16x16x32_bf16 v[64:67], v[120:123], v[204:207], v[64:67]
	v_mfma_f32_16x16x32_bf16 v[148:151], v[116:119], v[184:187], v[148:151]
	v_mfma_f32_16x16x32_bf16 v[140:143], v[124:127], v[184:187], v[140:143]
	v_mfma_f32_16x16x32_bf16 v[132:135], v[116:119], v[192:195], v[132:135]
	v_mfma_f32_16x16x32_bf16 v[128:131], v[124:127], v[192:195], v[128:131]
	v_mfma_f32_16x16x32_bf16 v[84:87], v[116:119], v[200:203], v[84:87]
	v_mfma_f32_16x16x32_bf16 v[76:79], v[124:127], v[200:203], v[76:79]
	v_mfma_f32_16x16x32_bf16 v[68:71], v[116:119], v[208:211], v[68:71]
	v_mfma_f32_16x16x32_bf16 v[64:67], v[124:127], v[208:211], v[64:67]
	s_setprio 0
	s_barrier
; #define PG8_STAGE(bufoff, gbase, voff) do { _Pragma("unroll") for (int _i = 0; _i < 2; ++_i) \
;         __builtin_amdgcn_global_load_lds((const unsigned*)((const char*)(gbase) + (voff)[_i]), (LAS unsigned*)(lds + (bufoff) + ldsw + _i * 8192), 16, 0, 0); } while (0)
; #define PG8_LDA(dst, b, h) do { _Pragma("unroll") for (int m = 0; m < 4; ++m) _Pragma("unroll") for (int k = 0; k < 2; ++k) dst[m][k] = *(const LAS bf16x8*)(lds + PG8_SA(b, h) + aoff + m * 2048 + k * 1024); } while (0)
; #define PG8_MMA(ai, bj, At, Bt) do { __builtin_amdgcn_s_setprio(1); _Pragma("unroll") for (int m = 0; m < 4; ++m) _Pragma("unroll") for (int n = 0; n < 2; ++n) _Pragma("unroll") for (int k = 0; k < 2; ++k) \
;         acc[ai][bj][m][n] = __builtin_amdgcn_mfma_f32_16x16x32_bf16(Bt[n][k], At[m][k], acc[ai][bj][m][n], 0, 0, 0); __builtin_amdgcn_s_setprio(0); } while (0)
; #define PG8_WAIT_V(n) asm volatile("s_waitcnt vmcnt(" #n ")" ::: "memory")
; #define PG8_WAIT_L(n) asm volatile("s_waitcnt lgkmcnt(" #n ")" ::: "memory")
; #define PG8_BAR __builtin_amdgcn_s_barrier()
; #define PG8_SCHED __builtin_amdgcn_sched_barrier(0)
; template <class Sched, class Epi, bool ALIGN_EPI, bool SP2>
; __device__ __forceinline__ void gemm_phase(LAS unsigned char* lds, const int K, const int lda, const int ldb, const Sched& S, const Epi& E) {
;     ...
;         for (int t = 0; t < nt; t += 2) {
;             const bool last = (t == nt - 2);
;             const char* a1 = cA + (size_t)(t + 1) * kstep;
;             const char* a2 = last ? nA : cA + (size_t)(t + 2) * kstep; const char* b2 = last ? nB : cB + (size_t)(t + 2) * kstep;
;     ...
;             PG8_LDA(At, 1, 1); PG8_STAGE(PG8_SB(1, 0), b3, voffB); PG8_STAGE(PG8_SB(1, 1), b3 + hstepB, voffB); PG8_STAGE(PG8_SA(1, 0), a3, voffA);
;             PG8_WAIT_V(8); PG8_WAIT_L(0); PG8_BAR; PG8_MMA(1, 0, At, B0); PG8_MMA(1, 1, At, B1); PG8_BAR; PG8_SCHED;
	s_add_i32 s0, s52, s15
	v_lshl_add_u64 v[172:173], v[172:173], 0, s[10:11]
	s_mov_b32 m0, s0
	ds_read_b128 v[168:171], v181 offset:49152
	ds_read_b128 v[184:187], v181 offset:50176
	ds_read_b128 v[188:191], v181 offset:51200
	ds_read_b128 v[192:195], v181 offset:52224
	ds_read_b128 v[196:199], v181 offset:53248
	ds_read_b128 v[200:203], v181 offset:54272
	ds_read_b128 v[204:207], v181 offset:55296
	ds_read_b128 v[208:211], v181 offset:56320
	global_load_lds_dwordx4 v[172:173], off
	s_add_i32 m0, s0, 0x2000
	s_add_u32 s0, s24, 0x160080
	v_lshl_add_u64 v[172:173], v[212:213], 0, s[10:11]
	s_addc_u32 s1, s25, 0
	s_add_i32 s24, s53, s15
	global_load_lds_dwordx4 v[172:173], off
	v_lshl_add_u64 v[172:173], s[0:1], 0, v[160:161]
	s_mov_b32 m0, s24
	s_nop 0
	global_load_lds_dwordx4 v[172:173], off
	v_lshl_add_u64 v[172:173], s[0:1], 0, v[162:163]
	s_add_i32 m0, s24, 0x2000
	s_nop 0
	global_load_lds_dwordx4 v[172:173], off
	v_lshl_add_u64 v[172:173], v[214:215], 0, s[10:11]
	s_mov_b32 m0, s36
	s_nop 0
	global_load_lds_dwordx4 v[172:173], off
	v_lshl_add_u64 v[172:173], v[216:217], 0, s[10:11]
	s_mov_b32 m0, s37
	s_nop 0
	global_load_lds_dwordx4 v[172:173], off
	s_waitcnt vmcnt(8)
	s_waitcnt lgkmcnt(0)
	s_barrier
	s_setprio 1
	s_waitcnt lgkmcnt(0)
	v_mfma_f32_16x16x32_bf16 v[60:63], v[96:99], v[168:171], v[60:63]
	v_mfma_f32_16x16x32_bf16 v[56:59], v[104:107], v[168:171], v[56:59]
	v_mfma_f32_16x16x32_bf16 v[48:51], v[96:99], v[188:191], v[48:51]
	v_mfma_f32_16x16x32_bf16 v[40:43], v[104:107], v[188:191], v[40:43]
	v_mfma_f32_16x16x32_bf16 v[28:31], v[96:99], v[196:199], v[28:31]
	v_mfma_f32_16x16x32_bf16 v[24:27], v[104:107], v[196:199], v[24:27]
	v_mfma_f32_16x16x32_bf16 v[16:19], v[96:99], v[204:207], v[16:19]
	v_mfma_f32_16x16x32_bf16 v[8:11], v[104:107], v[204:207], v[8:11]
	v_mfma_f32_16x16x32_bf16 v[60:63], v[100:103], v[184:187], v[60:63]
	v_mfma_f32_16x16x32_bf16 v[56:59], v[108:111], v[184:187], v[56:59]
	v_mfma_f32_16x16x32_bf16 v[48:51], v[100:103], v[192:195], v[48:51]
	v_mfma_f32_16x16x32_bf16 v[40:43], v[108:111], v[192:195], v[40:43]
	v_mfma_f32_16x16x32_bf16 v[28:31], v[100:103], v[200:203], v[28:31]
	v_mfma_f32_16x16x32_bf16 v[24:27], v[108:111], v[200:203], v[24:27]
	v_mfma_f32_16x16x32_bf16 v[16:19], v[100:103], v[208:211], v[16:19]
	v_mfma_f32_16x16x32_bf16 v[8:11], v[108:111], v[208:211], v[8:11]
	s_setprio 0
	s_setprio 1
	v_mfma_f32_16x16x32_bf16 v[52:55], v[112:115], v[168:171], v[52:55]
	v_mfma_f32_16x16x32_bf16 v[44:47], v[120:123], v[168:171], v[44:47]
	v_mfma_f32_16x16x32_bf16 v[36:39], v[112:115], v[188:191], v[36:39]
	v_mfma_f32_16x16x32_bf16 v[32:35], v[120:123], v[188:191], v[32:35]
	v_mfma_f32_16x16x32_bf16 v[20:23], v[112:115], v[196:199], v[20:23]
	v_mfma_f32_16x16x32_bf16 v[12:15], v[120:123], v[196:199], v[12:15]
	v_mfma_f32_16x16x32_bf16 v[4:7], v[112:115], v[204:207], v[4:7]
	v_mfma_f32_16x16x32_bf16 v[0:3], v[120:123], v[204:207], v[0:3]
	v_mfma_f32_16x16x32_bf16 v[52:55], v[116:119], v[184:187], v[52:55]
	v_mfma_f32_16x16x32_bf16 v[44:47], v[124:127], v[184:187], v[44:47]
	v_mfma_f32_16x16x32_bf16 v[36:39], v[116:119], v[192:195], v[36:39]
	v_mfma_f32_16x16x32_bf16 v[32:35], v[124:127], v[192:195], v[32:35]
	v_mfma_f32_16x16x32_bf16 v[20:23], v[116:119], v[200:203], v[20:23]
	v_mfma_f32_16x16x32_bf16 v[12:15], v[124:127], v[200:203], v[12:15]
	v_mfma_f32_16x16x32_bf16 v[4:7], v[116:119], v[208:211], v[4:7]
	v_mfma_f32_16x16x32_bf16 v[0:3], v[124:127], v[208:211], v[0:3]
	s_setprio 0
	s_add_i32 s51, s51, 2
	s_add_u32 s49, s49, 0x100
	s_addc_u32 s50, s50, 0
	s_cmpk_gt_u32 s51, 0x55
	s_mov_b64 s[0:1], s[4:5]
	s_barrier
	s_cbranch_scc0 .LBB0_1120
	s_and_b64 vcc, exec, s[12:13]
	s_cbranch_vccz .LBB0_1123
	s_barrier
